# v043 + all six GEMM K-loops: 44 64-bit VALU address adds folded into the saddr form of global_load_lds (fewer VALU beside MFMAs)
# speedup vs baseline: 1.0085x; 1.0072x over previous
; #define PG8_STAGE(bufoff, gbase, voff) do { _Pragma("unroll") for (int _i = 0; _i < 2; ++_i) \
;         __builtin_amdgcn_global_load_lds((const unsigned*)((const char*)(gbase) + (voff)[_i]), (LAS unsigned*)(lds + (bufoff) + ldsw + _i * 8192), 16, 0, 0); } while (0)
; #define PG8_LDA(dst, b, h) do { _Pragma("unroll") for (int m = 0; m < 4; ++m) _Pragma("unroll") for (int k = 0; k < 2; ++k) dst[m][k] = *(const LAS bf16x8*)(lds + PG8_SA(b, h) + aoff + m * 2048 + k * 1024); } while (0)
; #define PG8_LDB(dst, b, h) do { _Pragma("unroll") for (int n = 0; n < 2; ++n) _Pragma("unroll") for (int k = 0; k < 2; ++k) dst[n][k] = *(const LAS bf16x8*)(lds + PG8_SB(b, h) + boff + n * 2048 + k * 1024); } while (0)
; #define PG8_MMA(ai, bj, At, Bt) do { __builtin_amdgcn_s_setprio(1); _Pragma("unroll") for (int m = 0; m < 4; ++m) _Pragma("unroll") for (int n = 0; n < 2; ++n) _Pragma("unroll") for (int k = 0; k < 2; ++k) \
;         acc[ai][bj][m][n] = __builtin_amdgcn_mfma_f32_16x16x32_bf16(Bt[n][k], At[m][k], acc[ai][bj][m][n], 0, 0, 0); __builtin_amdgcn_s_setprio(0); } while (0)
; #define PG8_WAIT_V(n) asm volatile("s_waitcnt vmcnt(" #n ")" ::: "memory")
; #define PG8_WAIT_L(n) asm volatile("s_waitcnt lgkmcnt(" #n ")" ::: "memory")
; template <class Epi, class Sched, bool APERM = false, bool HALFN = false>
; __device__ __forceinline__ void gemm_phase(LAS unsigned char* lds, const int tid_in, const int K, const Sched& S, const Epi& E) {
;     ...
;     for (;;) {
;         const bool has_next = S.next(ui + 1, nxt);
;         const char* nA = has_next ? nxt.A : cA; const char* nB = has_next ? nxt.B : cB;
;         for (int t = 0; t < nt; t += 2) {
;             const bool last = (t == nt - 2);
;             const char* a1 = cA + (size_t)(t + 1) * kstep;
;             const char* a2 = last ? nA : cA + (size_t)(t + 2) * kstep; const char* b2 = last ? nB : cB + (size_t)(t + 2) * kstep;
;             const char* a3 = a2 + kstep; const char* b3 = b2 + kstep;
;             PG8_LDB(B0, 0, 0); PG8_LDB(B1, 0, 1); PG8_SCHED; PG8_LDA(At, 0, 0); PG8_STAGE(PG8_SA(1, 1), a1 + hstepA, voffA);
;             PG8_WAIT_V(8); PG8_WAIT_L(0); PG8_BAR; PG8_MMA(0, 0, At, B0); if constexpr (!HALFN) PG8_MMA(0, 1, At, B1); PG8_BAR; PG8_SCHED;
;             PG8_LDA(At, 0, 1); PG8_STAGE(PG8_SB(0, 0), b2, voffB); PG8_STAGE(PG8_SB(0, 1), b2 + hstep, voffB); PG8_STAGE(PG8_SA(0, 0), a2, voffA);
.Lpfb_done:
.LBB0_346:
	s_add_u32 s4, s0, 0xfff80080
	s_addc_u32 s5, s1, -1
	s_add_i32 s44, 0, 0x10000
	s_cmp_eq_u32 s25, 28
	s_cselect_b32 s17, s19, s5
	s_cselect_b32 s16, s20, s4
	s_cselect_b32 s5, s21, s24
	s_cselect_b32 s4, s22, s23
	s_add_i32 s52, 0, 0x14000
	v_add_u32_e32 v180, s44, v139
	v_add_u32_e32 v196, s52, v139
	ds_read_b128 v[168:171], v180
	ds_read_b128 v[172:175], v180 offset:1024
	ds_read_b128 v[176:179], v180 offset:2048
	ds_read_b128 v[180:183], v180 offset:3072
	ds_read_b128 v[184:187], v196
	ds_read_b128 v[188:191], v196 offset:1024
	ds_read_b128 v[192:195], v196 offset:2048
	ds_read_b128 v[196:199], v196 offset:3072
	s_add_i32 m0, s38, 0xc000
	ds_read_b128 v[204:207], v141
	ds_read_b128 v[208:211], v141 offset:1024
	ds_read_b128 v[212:215], v141 offset:2048
	ds_read_b128 v[216:219], v141 offset:3072
	ds_read_b128 v[220:223], v141 offset:4096
	ds_read_b128 v[224:227], v141 offset:5120
	ds_read_b128 v[228:231], v141 offset:6144
	ds_read_b128 v[244:247], v141 offset:7168
	global_load_lds_dwordx4 v166, s[0:1]
	s_add_i32 m0, s38, 0xe000
	s_nop 0
	global_load_lds_dwordx4 v164, s[0:1]
	s_waitcnt vmcnt(8)
	s_waitcnt lgkmcnt(0)
	s_barrier
	s_setprio 1
	s_waitcnt lgkmcnt(0)
	v_mfma_f32_16x16x32_bf16 v[124:127], v[168:171], v[204:207], v[124:127]
	v_mfma_f32_16x16x32_bf16 v[120:123], v[176:179], v[204:207], v[120:123]
	v_mfma_f32_16x16x32_bf16 v[108:111], v[168:171], v[212:215], v[108:111]
	v_mfma_f32_16x16x32_bf16 v[104:107], v[176:179], v[212:215], v[104:107]
	v_mfma_f32_16x16x32_bf16 v[92:95], v[168:171], v[220:223], v[92:95]
	v_mfma_f32_16x16x32_bf16 v[88:91], v[176:179], v[220:223], v[88:91]
	v_mfma_f32_16x16x32_bf16 v[76:79], v[168:171], v[228:231], v[76:79]
	v_mfma_f32_16x16x32_bf16 v[72:75], v[176:179], v[228:231], v[72:75]
	v_mfma_f32_16x16x32_bf16 v[124:127], v[172:175], v[208:211], v[124:127]
	v_mfma_f32_16x16x32_bf16 v[120:123], v[180:183], v[208:211], v[120:123]
	v_mfma_f32_16x16x32_bf16 v[108:111], v[172:175], v[216:219], v[108:111]
	v_mfma_f32_16x16x32_bf16 v[104:107], v[180:183], v[216:219], v[104:107]
	v_mfma_f32_16x16x32_bf16 v[92:95], v[172:175], v[224:227], v[92:95]
	v_mfma_f32_16x16x32_bf16 v[88:91], v[180:183], v[224:227], v[88:91]
	v_mfma_f32_16x16x32_bf16 v[76:79], v[172:175], v[244:247], v[76:79]
	v_mfma_f32_16x16x32_bf16 v[72:75], v[180:183], v[244:247], v[72:75]
	s_setprio 0
	s_setprio 1
	v_mfma_f32_16x16x32_bf16 v[116:119], v[184:187], v[204:207], v[116:119]
	v_mfma_f32_16x16x32_bf16 v[112:115], v[192:195], v[204:207], v[112:115]
	v_mfma_f32_16x16x32_bf16 v[100:103], v[184:187], v[212:215], v[100:103]
	v_mfma_f32_16x16x32_bf16 v[96:99], v[192:195], v[212:215], v[96:99]
	v_mfma_f32_16x16x32_bf16 v[84:87], v[184:187], v[220:223], v[84:87]
	v_mfma_f32_16x16x32_bf16 v[80:83], v[192:195], v[220:223], v[80:83]
	v_mfma_f32_16x16x32_bf16 v[68:71], v[184:187], v[228:231], v[68:71]
	v_mfma_f32_16x16x32_bf16 v[64:67], v[192:195], v[228:231], v[64:67]
	v_mfma_f32_16x16x32_bf16 v[116:119], v[188:191], v[208:211], v[116:119]
	v_mfma_f32_16x16x32_bf16 v[112:115], v[196:199], v[208:211], v[112:115]
	v_mfma_f32_16x16x32_bf16 v[100:103], v[188:191], v[216:219], v[100:103]
	v_mfma_f32_16x16x32_bf16 v[96:99], v[196:199], v[216:219], v[96:99]
	v_mfma_f32_16x16x32_bf16 v[84:87], v[188:191], v[224:227], v[84:87]
	v_mfma_f32_16x16x32_bf16 v[80:83], v[196:199], v[224:227], v[80:83]
	v_mfma_f32_16x16x32_bf16 v[68:71], v[188:191], v[244:247], v[68:71]
	v_mfma_f32_16x16x32_bf16 v[64:67], v[196:199], v[244:247], v[64:67]
	s_setprio 0
	s_barrier
	s_add_i32 s44, s44, s35
	v_lshl_add_u64 v[232:233], s[4:5], 0, v[130:131]
	s_mov_b32 m0, s44
	ds_read_b128 v[204:207], v141 offset:16384
	ds_read_b128 v[208:211], v141 offset:17408
	ds_read_b128 v[212:215], v141 offset:18432
	ds_read_b128 v[216:219], v141 offset:19456
	ds_read_b128 v[220:223], v141 offset:20480
	ds_read_b128 v[224:227], v141 offset:21504
	ds_read_b128 v[228:231], v141 offset:22528
	ds_read_b128 v[244:247], v141 offset:23552
	global_load_lds_dwordx4 v[232:233], off
	s_add_i32 m0, s44, 0x2000
	s_add_u32 s44, s4, 0x80000
	v_lshl_add_u64 v[248:249], s[4:5], 0, v[134:135]
	s_addc_u32 s45, s5, 0
	s_add_i32 s52, s52, s35
	global_load_lds_dwordx4 v[248:249], off
	s_mov_b32 m0, s52
	v_lshl_add_u64 v[252:253], s[16:17], 0, v[132:133]
	global_load_lds_dwordx4 v130, s[44:45]
	s_add_i32 m0, s52, 0x2000
	s_nop 0
	global_load_lds_dwordx4 v134, s[44:45]
	v_lshl_add_u64 v[250:251], s[16:17], 0, v[128:129]
	s_mov_b32 m0, s38
	s_nop 0
	global_load_lds_dwordx4 v[250:251], off
	s_mov_b32 m0, s39
	s_nop 0
	global_load_lds_dwordx4 v[252:253], off
	s_waitcnt vmcnt(8)
	s_waitcnt lgkmcnt(0)
	s_barrier
; #define PG8_STAGE(bufoff, gbase, voff) do { _Pragma("unroll") for (int _i = 0; _i < 2; ++_i) \
;         __builtin_amdgcn_global_load_lds((const unsigned*)((const char*)(gbase) + (voff)[_i]), (LAS unsigned*)(lds + (bufoff) + ldsw + _i * 8192), 16, 0, 0); } while (0)
; #define PG8_LDA(dst, b, h) do { _Pragma("unroll") for (int m = 0; m < 4; ++m) _Pragma("unroll") for (int k = 0; k < 2; ++k) dst[m][k] = *(const LAS bf16x8*)(lds + PG8_SA(b, h) + aoff + m * 2048 + k * 1024); } while (0)
; #define PG8_LDB(dst, b, h) do { _Pragma("unroll") for (int n = 0; n < 2; ++n) _Pragma("unroll") for (int k = 0; k < 2; ++k) dst[n][k] = *(const LAS bf16x8*)(lds + PG8_SB(b, h) + boff + n * 2048 + k * 1024); } while (0)
; #define PG8_MMA(ai, bj, At, Bt) do { __builtin_amdgcn_s_setprio(1); _Pragma("unroll") for (int m = 0; m < 4; ++m) _Pragma("unroll") for (int n = 0; n < 2; ++n) _Pragma("unroll") for (int k = 0; k < 2; ++k) \
;         acc[ai][bj][m][n] = __builtin_amdgcn_mfma_f32_16x16x32_bf16(Bt[n][k], At[m][k], acc[ai][bj][m][n], 0, 0, 0); __builtin_amdgcn_s_setprio(0); } while (0)
; #define PG8_WAIT_V(n) asm volatile("s_waitcnt vmcnt(" #n ")" ::: "memory")
; #define PG8_WAIT_L(n) asm volatile("s_waitcnt lgkmcnt(" #n ")" ::: "memory")
; #define PG8_BAR __builtin_amdgcn_s_barrier()
; #define PG8_SCHED __builtin_amdgcn_sched_barrier(0)
; template <class Epi, class Sched, bool APERM = false, bool HALFN = false>
; __device__ __forceinline__ void gemm_phase(LAS unsigned char* lds, const int tid_in, const int K, const Sched& S, const Epi& E) {
;     ...
;             PG8_WAIT_V(8); PG8_WAIT_L(0); PG8_BAR; PG8_MMA(1, 0, At, B0); if constexpr (!HALFN) PG8_MMA(1, 1, At, B1); PG8_BAR; PG8_SCHED;
;             PG8_LDB(B0, 1, 0); PG8_LDB(B1, 1, 1); PG8_SCHED; PG8_LDA(At, 1, 0); PG8_STAGE(PG8_SA(0, 1), a2 + hstepA, voffA);
;             PG8_WAIT_V(8); PG8_WAIT_L(0); PG8_BAR; PG8_MMA(0, 0, At, B0); if constexpr (!HALFN) PG8_MMA(0, 1, At, B1); PG8_BAR; PG8_SCHED;
	s_setprio 1
	s_waitcnt lgkmcnt(0)
	v_mfma_f32_16x16x32_bf16 v[60:63], v[168:171], v[204:207], v[60:63]
	v_mfma_f32_16x16x32_bf16 v[56:59], v[176:179], v[204:207], v[56:59]
	v_mfma_f32_16x16x32_bf16 v[44:47], v[168:171], v[212:215], v[44:47]
	v_mfma_f32_16x16x32_bf16 v[40:43], v[176:179], v[212:215], v[40:43]
	v_mfma_f32_16x16x32_bf16 v[28:31], v[168:171], v[220:223], v[28:31]
	v_mfma_f32_16x16x32_bf16 v[24:27], v[176:179], v[220:223], v[24:27]
	v_mfma_f32_16x16x32_bf16 v[12:15], v[168:171], v[228:231], v[12:15]
	v_mfma_f32_16x16x32_bf16 v[8:11], v[176:179], v[228:231], v[8:11]
	v_mfma_f32_16x16x32_bf16 v[60:63], v[172:175], v[208:211], v[60:63]
	v_mfma_f32_16x16x32_bf16 v[56:59], v[180:183], v[208:211], v[56:59]
	v_mfma_f32_16x16x32_bf16 v[44:47], v[172:175], v[216:219], v[44:47]
	v_mfma_f32_16x16x32_bf16 v[40:43], v[180:183], v[216:219], v[40:43]
	v_mfma_f32_16x16x32_bf16 v[28:31], v[172:175], v[224:227], v[28:31]
	v_mfma_f32_16x16x32_bf16 v[24:27], v[180:183], v[224:227], v[24:27]
	v_mfma_f32_16x16x32_bf16 v[12:15], v[172:175], v[244:247], v[12:15]
	v_mfma_f32_16x16x32_bf16 v[8:11], v[180:183], v[244:247], v[8:11]
	s_setprio 0
	s_setprio 1
	v_mfma_f32_16x16x32_bf16 v[52:55], v[184:187], v[204:207], v[52:55]
	v_mfma_f32_16x16x32_bf16 v[48:51], v[192:195], v[204:207], v[48:51]
	v_mfma_f32_16x16x32_bf16 v[36:39], v[184:187], v[212:215], v[36:39]
	v_mfma_f32_16x16x32_bf16 v[32:35], v[192:195], v[212:215], v[32:35]
	v_mfma_f32_16x16x32_bf16 v[20:23], v[184:187], v[220:223], v[20:23]
	v_mfma_f32_16x16x32_bf16 v[16:19], v[192:195], v[220:223], v[16:19]
	v_mfma_f32_16x16x32_bf16 v[4:7], v[184:187], v[228:231], v[4:7]
	v_mfma_f32_16x16x32_bf16 v[0:3], v[192:195], v[228:231], v[0:3]
	v_mfma_f32_16x16x32_bf16 v[52:55], v[188:191], v[208:211], v[52:55]
	v_mfma_f32_16x16x32_bf16 v[48:51], v[196:199], v[208:211], v[48:51]
	v_mfma_f32_16x16x32_bf16 v[36:39], v[188:191], v[216:219], v[36:39]
	v_mfma_f32_16x16x32_bf16 v[32:35], v[196:199], v[216:219], v[32:35]
	v_mfma_f32_16x16x32_bf16 v[20:23], v[188:191], v[224:227], v[20:23]
	v_mfma_f32_16x16x32_bf16 v[16:19], v[196:199], v[224:227], v[16:19]
	v_mfma_f32_16x16x32_bf16 v[4:7], v[188:191], v[244:247], v[4:7]
	v_mfma_f32_16x16x32_bf16 v[0:3], v[196:199], v[244:247], v[0:3]
	s_setprio 0
	s_barrier
	s_add_i32 s44, 0, 0x18000
	s_add_i32 s45, 0, 0x1c000
	v_add_u32_e32 v180, s44, v139
	v_add_u32_e32 v196, s45, v139
	ds_read_b128 v[168:171], v180
	ds_read_b128 v[172:175], v180 offset:1024
	ds_read_b128 v[176:179], v180 offset:2048
	ds_read_b128 v[180:183], v180 offset:3072
	ds_read_b128 v[184:187], v196
	ds_read_b128 v[188:191], v196 offset:1024
	ds_read_b128 v[192:195], v196 offset:2048
	ds_read_b128 v[196:199], v196 offset:3072
	s_add_u32 s16, s16, 0x80000
	s_addc_u32 s17, s17, 0
	s_mov_b32 m0, s57
	ds_read_b128 v[204:207], v141 offset:32768
	ds_read_b128 v[208:211], v141 offset:33792
	ds_read_b128 v[212:215], v141 offset:34816
	ds_read_b128 v[216:219], v141 offset:35840
	ds_read_b128 v[220:223], v141 offset:36864
	ds_read_b128 v[224:227], v141 offset:37888
	ds_read_b128 v[228:231], v141 offset:38912
	ds_read_b128 v[244:247], v141 offset:39936
	global_load_lds_dwordx4 v128, s[16:17]
	s_mov_b32 m0, s70
	s_nop 0
	global_load_lds_dwordx4 v132, s[16:17]
	s_waitcnt vmcnt(8)
	s_waitcnt lgkmcnt(0)
	s_barrier
	s_setprio 1
	s_waitcnt lgkmcnt(0)
	v_mfma_f32_16x16x32_bf16 v[124:127], v[168:171], v[204:207], v[124:127]
	v_mfma_f32_16x16x32_bf16 v[120:123], v[176:179], v[204:207], v[120:123]
	v_mfma_f32_16x16x32_bf16 v[108:111], v[168:171], v[212:215], v[108:111]
	v_mfma_f32_16x16x32_bf16 v[104:107], v[176:179], v[212:215], v[104:107]
	v_mfma_f32_16x16x32_bf16 v[92:95], v[168:171], v[220:223], v[92:95]
	v_mfma_f32_16x16x32_bf16 v[88:91], v[176:179], v[220:223], v[88:91]
	v_mfma_f32_16x16x32_bf16 v[76:79], v[168:171], v[228:231], v[76:79]
	v_mfma_f32_16x16x32_bf16 v[72:75], v[176:179], v[228:231], v[72:75]
	v_mfma_f32_16x16x32_bf16 v[124:127], v[172:175], v[208:211], v[124:127]
	v_mfma_f32_16x16x32_bf16 v[120:123], v[180:183], v[208:211], v[120:123]
	v_mfma_f32_16x16x32_bf16 v[108:111], v[172:175], v[216:219], v[108:111]
	v_mfma_f32_16x16x32_bf16 v[104:107], v[180:183], v[216:219], v[104:107]
	v_mfma_f32_16x16x32_bf16 v[92:95], v[172:175], v[224:227], v[92:95]
	v_mfma_f32_16x16x32_bf16 v[88:91], v[180:183], v[224:227], v[88:91]
	v_mfma_f32_16x16x32_bf16 v[76:79], v[172:175], v[244:247], v[76:79]
	v_mfma_f32_16x16x32_bf16 v[72:75], v[180:183], v[244:247], v[72:75]
	s_setprio 0
	s_setprio 1
	v_mfma_f32_16x16x32_bf16 v[116:119], v[184:187], v[204:207], v[116:119]
	v_mfma_f32_16x16x32_bf16 v[112:115], v[192:195], v[204:207], v[112:115]
	v_mfma_f32_16x16x32_bf16 v[100:103], v[184:187], v[212:215], v[100:103]
	v_mfma_f32_16x16x32_bf16 v[96:99], v[192:195], v[212:215], v[96:99]
	v_mfma_f32_16x16x32_bf16 v[84:87], v[184:187], v[220:223], v[84:87]
	v_mfma_f32_16x16x32_bf16 v[80:83], v[192:195], v[220:223], v[80:83]
	v_mfma_f32_16x16x32_bf16 v[68:71], v[184:187], v[228:231], v[68:71]
	v_mfma_f32_16x16x32_bf16 v[64:67], v[192:195], v[228:231], v[64:67]
	v_mfma_f32_16x16x32_bf16 v[116:119], v[188:191], v[208:211], v[116:119]
	v_mfma_f32_16x16x32_bf16 v[112:115], v[196:199], v[208:211], v[112:115]
	v_mfma_f32_16x16x32_bf16 v[100:103], v[188:191], v[216:219], v[100:103]
	v_mfma_f32_16x16x32_bf16 v[96:99], v[196:199], v[216:219], v[96:99]
	v_mfma_f32_16x16x32_bf16 v[84:87], v[188:191], v[224:227], v[84:87]
	v_mfma_f32_16x16x32_bf16 v[80:83], v[196:199], v[224:227], v[80:83]
	v_mfma_f32_16x16x32_bf16 v[68:71], v[188:191], v[244:247], v[68:71]
	v_mfma_f32_16x16x32_bf16 v[64:67], v[196:199], v[244:247], v[64:67]
	s_setprio 0
	s_barrier
; #define PG8_STAGE(bufoff, gbase, voff) do { _Pragma("unroll") for (int _i = 0; _i < 2; ++_i) \
;         __builtin_amdgcn_global_load_lds((const unsigned*)((const char*)(gbase) + (voff)[_i]), (LAS unsigned*)(lds + (bufoff) + ldsw + _i * 8192), 16, 0, 0); } while (0)
; #define PG8_LDA(dst, b, h) do { _Pragma("unroll") for (int m = 0; m < 4; ++m) _Pragma("unroll") for (int k = 0; k < 2; ++k) dst[m][k] = *(const LAS bf16x8*)(lds + PG8_SA(b, h) + aoff + m * 2048 + k * 1024); } while (0)
; #define PG8_MMA(ai, bj, At, Bt) do { __builtin_amdgcn_s_setprio(1); _Pragma("unroll") for (int m = 0; m < 4; ++m) _Pragma("unroll") for (int n = 0; n < 2; ++n) _Pragma("unroll") for (int k = 0; k < 2; ++k) \
;         acc[ai][bj][m][n] = __builtin_amdgcn_mfma_f32_16x16x32_bf16(Bt[n][k], At[m][k], acc[ai][bj][m][n], 0, 0, 0); __builtin_amdgcn_s_setprio(0); } while (0)
; #define PG8_WAIT_V(n) asm volatile("s_waitcnt vmcnt(" #n ")" ::: "memory")
; #define PG8_WAIT_L(n) asm volatile("s_waitcnt lgkmcnt(" #n ")" ::: "memory")
; #define PG8_BAR __builtin_amdgcn_s_barrier()
; #define PG8_SCHED __builtin_amdgcn_sched_barrier(0)
; template <class Epi, class Sched, bool APERM = false, bool HALFN = false>
; __device__ __forceinline__ void gemm_phase(LAS unsigned char* lds, const int tid_in, const int K, const Sched& S, const Epi& E) {
;     ...
;             PG8_LDA(At, 1, 1); PG8_STAGE(PG8_SB(1, 0), b3, voffB); PG8_STAGE(PG8_SB(1, 1), b3 + hstep, voffB); PG8_STAGE(PG8_SA(1, 0), a3, voffA);
;             PG8_WAIT_V(8); PG8_WAIT_L(0); PG8_BAR; PG8_MMA(1, 0, At, B0); if constexpr (!HALFN) PG8_MMA(1, 1, At, B1); PG8_BAR; PG8_SCHED;
;         }
;         if (wr == 0) PG8_BAR;
	s_add_i32 s16, s44, s35
	v_lshl_add_u64 v[232:233], v[232:233], 0, s[78:79]
	s_mov_b32 m0, s16
	ds_read_b128 v[204:207], v141 offset:49152
	ds_read_b128 v[208:211], v141 offset:50176
	ds_read_b128 v[212:215], v141 offset:51200
	ds_read_b128 v[216:219], v141 offset:52224
	ds_read_b128 v[220:223], v141 offset:53248
	ds_read_b128 v[224:227], v141 offset:54272
	ds_read_b128 v[228:231], v141 offset:55296
	ds_read_b128 v[244:247], v141 offset:56320
	global_load_lds_dwordx4 v[232:233], off
	s_add_i32 m0, s16, 0x2000
	s_add_u32 s4, s4, 0x80080
	v_lshl_add_u64 v[232:233], v[248:249], 0, s[78:79]
	s_addc_u32 s5, s5, 0
	s_add_i32 s16, s45, s35
	global_load_lds_dwordx4 v[232:233], off
	s_mov_b32 m0, s16
	s_nop 0
	global_load_lds_dwordx4 v130, s[4:5]
	s_add_i32 m0, s16, 0x2000
	s_nop 0
	global_load_lds_dwordx4 v134, s[4:5]
	v_lshl_add_u64 v[232:233], v[250:251], 0, s[78:79]
	s_mov_b32 m0, s71
	s_nop 0
	global_load_lds_dwordx4 v[232:233], off
	v_lshl_add_u64 v[232:233], v[252:253], 0, s[78:79]
	s_mov_b32 m0, s74
	s_nop 0
	global_load_lds_dwordx4 v[232:233], off
	s_waitcnt vmcnt(8)
	s_waitcnt lgkmcnt(0)
	s_barrier
	s_setprio 1
	s_waitcnt lgkmcnt(0)
	v_mfma_f32_16x16x32_bf16 v[60:63], v[168:171], v[204:207], v[60:63]
	v_mfma_f32_16x16x32_bf16 v[56:59], v[176:179], v[204:207], v[56:59]
	v_mfma_f32_16x16x32_bf16 v[44:47], v[168:171], v[212:215], v[44:47]
	v_mfma_f32_16x16x32_bf16 v[40:43], v[176:179], v[212:215], v[40:43]
	v_mfma_f32_16x16x32_bf16 v[28:31], v[168:171], v[220:223], v[28:31]
	v_mfma_f32_16x16x32_bf16 v[24:27], v[176:179], v[220:223], v[24:27]
	v_mfma_f32_16x16x32_bf16 v[12:15], v[168:171], v[228:231], v[12:15]
	v_mfma_f32_16x16x32_bf16 v[8:11], v[176:179], v[228:231], v[8:11]
	v_mfma_f32_16x16x32_bf16 v[60:63], v[172:175], v[208:211], v[60:63]
	v_mfma_f32_16x16x32_bf16 v[56:59], v[180:183], v[208:211], v[56:59]
	v_mfma_f32_16x16x32_bf16 v[44:47], v[172:175], v[216:219], v[44:47]
	v_mfma_f32_16x16x32_bf16 v[40:43], v[180:183], v[216:219], v[40:43]
	v_mfma_f32_16x16x32_bf16 v[28:31], v[172:175], v[224:227], v[28:31]
	v_mfma_f32_16x16x32_bf16 v[24:27], v[180:183], v[224:227], v[24:27]
	v_mfma_f32_16x16x32_bf16 v[12:15], v[172:175], v[244:247], v[12:15]
	v_mfma_f32_16x16x32_bf16 v[8:11], v[180:183], v[244:247], v[8:11]
	s_setprio 0
	s_setprio 1
	v_mfma_f32_16x16x32_bf16 v[52:55], v[184:187], v[204:207], v[52:55]
	v_mfma_f32_16x16x32_bf16 v[48:51], v[192:195], v[204:207], v[48:51]
	v_mfma_f32_16x16x32_bf16 v[36:39], v[184:187], v[212:215], v[36:39]
	v_mfma_f32_16x16x32_bf16 v[32:35], v[192:195], v[212:215], v[32:35]
	v_mfma_f32_16x16x32_bf16 v[20:23], v[184:187], v[220:223], v[20:23]
	v_mfma_f32_16x16x32_bf16 v[16:19], v[192:195], v[220:223], v[16:19]
	v_mfma_f32_16x16x32_bf16 v[4:7], v[184:187], v[228:231], v[4:7]
	v_mfma_f32_16x16x32_bf16 v[0:3], v[192:195], v[228:231], v[0:3]
	v_mfma_f32_16x16x32_bf16 v[52:55], v[188:191], v[208:211], v[52:55]
	v_mfma_f32_16x16x32_bf16 v[48:51], v[196:199], v[208:211], v[48:51]
	v_mfma_f32_16x16x32_bf16 v[36:39], v[188:191], v[216:219], v[36:39]
	v_mfma_f32_16x16x32_bf16 v[32:35], v[196:199], v[216:219], v[32:35]
	v_mfma_f32_16x16x32_bf16 v[20:23], v[188:191], v[224:227], v[20:23]
	v_mfma_f32_16x16x32_bf16 v[16:19], v[196:199], v[224:227], v[16:19]
	v_mfma_f32_16x16x32_bf16 v[4:7], v[188:191], v[244:247], v[4:7]
	v_mfma_f32_16x16x32_bf16 v[0:3], v[196:199], v[244:247], v[0:3]
	s_setprio 0
	s_barrier
	s_add_i32 s25, s25, 2
	s_add_u32 s23, s23, 0x100
	s_addc_u32 s24, s24, 0
	s_add_u32 s0, s0, 0x100
	s_addc_u32 s1, s1, 0
	s_cmp_gt_u32 s25, 29
	s_cbranch_scc0 .LBB0_346
	s_and_b64 vcc, exec, s[6:7]
	s_cbranch_vccz .LBB0_349
	s_barrier

; #define PG8_STAGE(bufoff, gbase, voff) do { _Pragma("unroll") for (int _i = 0; _i < 2; ++_i) \
;         __builtin_amdgcn_global_load_lds((const unsigned*)((const char*)(gbase) + (voff)[_i]), (LAS unsigned*)(lds + (bufoff) + ldsw + _i * 8192), 16, 0, 0); } while (0)
; #define PG8_LDA(dst, b, h) do { _Pragma("unroll") for (int m = 0; m < 4; ++m) _Pragma("unroll") for (int k = 0; k < 2; ++k) dst[m][k] = *(const LAS bf16x8*)(lds + PG8_SA(b, h) + aoff + m * 2048 + k * 1024); } while (0)
; #define PG8_LDB(dst, b, h) do { _Pragma("unroll") for (int n = 0; n < 2; ++n) _Pragma("unroll") for (int k = 0; k < 2; ++k) dst[n][k] = *(const LAS bf16x8*)(lds + PG8_SB(b, h) + boff + n * 2048 + k * 1024); } while (0)
; #define PG8_MMA(ai, bj, At, Bt) do { __builtin_amdgcn_s_setprio(1); _Pragma("unroll") for (int m = 0; m < 4; ++m) _Pragma("unroll") for (int n = 0; n < 2; ++n) _Pragma("unroll") for (int k = 0; k < 2; ++k) \
;         acc[ai][bj][m][n] = __builtin_amdgcn_mfma_f32_16x16x32_bf16(Bt[n][k], At[m][k], acc[ai][bj][m][n], 0, 0, 0); __builtin_amdgcn_s_setprio(0); } while (0)
; #define PG8_WAIT_V(n) asm volatile("s_waitcnt vmcnt(" #n ")" ::: "memory")
; #define PG8_WAIT_L(n) asm volatile("s_waitcnt lgkmcnt(" #n ")" ::: "memory")
; template <class Epi, class Sched, bool APERM = false, bool HALFN = false>
; __device__ __forceinline__ void gemm_phase(LAS unsigned char* lds, const int tid_in, const int K, const Sched& S, const Epi& E) {
;     ...
;     for (;;) {
;         const bool has_next = S.next(ui + 1, nxt);
;         const char* nA = has_next ? nxt.A : cA; const char* nB = has_next ? nxt.B : cB;
;         for (int t = 0; t < nt; t += 2) {
;             const bool last = (t == nt - 2);
;             const char* a1 = cA + (size_t)(t + 1) * kstep;
;             const char* a2 = last ? nA : cA + (size_t)(t + 2) * kstep; const char* b2 = last ? nB : cB + (size_t)(t + 2) * kstep;
;             const char* a3 = a2 + kstep; const char* b3 = b2 + kstep;
;             PG8_LDB(B0, 0, 0); PG8_LDB(B1, 0, 1); PG8_SCHED; PG8_LDA(At, 0, 0); PG8_STAGE(PG8_SA(1, 1), a1 + hstepA, voffA);
;             PG8_WAIT_V(8); PG8_WAIT_L(0); PG8_BAR; PG8_MMA(0, 0, At, B0); if constexpr (!HALFN) PG8_MMA(0, 1, At, B1); PG8_BAR; PG8_SCHED;
;             PG8_LDA(At, 0, 1); PG8_STAGE(PG8_SB(0, 0), b2, voffB); PG8_STAGE(PG8_SB(0, 1), b2 + hstep, voffB); PG8_STAGE(PG8_SA(0, 0), a2, voffA);
.LBB0_682:
	s_add_u32 s18, s16, 0xfff80080
	s_addc_u32 s19, s17, -1
	s_add_i32 s57, 0, 0x10000
	s_cmp_eq_u32 s53, 28
	s_cselect_b32 s21, s11, s19
	s_cselect_b32 s20, s10, s18
	s_cselect_b32 s19, s13, s52
	s_cselect_b32 s18, s12, s45
	s_add_i32 s72, 0, 0x14000
	v_add_u32_e32 v128, s57, v220
	v_add_u32_e32 v156, s72, v220
	ds_read_b128 v[112:115], v128
	ds_read_b128 v[116:119], v128 offset:1024
	ds_read_b128 v[120:123], v128 offset:2048
	ds_read_b128 v[128:131], v128 offset:3072
	ds_read_b128 v[136:139], v156
	ds_read_b128 v[140:143], v156 offset:1024
	ds_read_b128 v[144:147], v156 offset:2048
	ds_read_b128 v[156:159], v156 offset:3072
	s_add_i32 m0, s29, 0xc000
	ds_read_b128 v[160:163], v226
	ds_read_b128 v[164:167], v226 offset:1024
	ds_read_b128 v[168:171], v226 offset:2048
	ds_read_b128 v[172:175], v226 offset:3072
	ds_read_b128 v[176:179], v226 offset:4096
	ds_read_b128 v[180:183], v226 offset:5120
	ds_read_b128 v[184:187], v226 offset:6144
	ds_read_b128 v[204:207], v226 offset:7168
	global_load_lds_dwordx4 v198, s[16:17]
	s_add_i32 m0, s29, 0xe000
	s_nop 0
	global_load_lds_dwordx4 v196, s[16:17]
	s_waitcnt vmcnt(8)
	s_waitcnt lgkmcnt(0)
	s_barrier
	s_setprio 1
	s_waitcnt lgkmcnt(0)
	v_mfma_f32_16x16x32_bf16 v[152:155], v[112:115], v[160:163], v[152:155]
	v_mfma_f32_16x16x32_bf16 v[148:151], v[120:123], v[160:163], v[148:151]
	v_mfma_f32_16x16x32_bf16 v[108:111], v[112:115], v[168:171], v[108:111]
	v_mfma_f32_16x16x32_bf16 v[104:107], v[120:123], v[168:171], v[104:107]
	v_mfma_f32_16x16x32_bf16 v[92:95], v[112:115], v[176:179], v[92:95]
	v_mfma_f32_16x16x32_bf16 v[88:91], v[120:123], v[176:179], v[88:91]
	v_mfma_f32_16x16x32_bf16 v[76:79], v[112:115], v[184:187], v[76:79]
	v_mfma_f32_16x16x32_bf16 v[72:75], v[120:123], v[184:187], v[72:75]
	v_mfma_f32_16x16x32_bf16 v[152:155], v[116:119], v[164:167], v[152:155]
	v_mfma_f32_16x16x32_bf16 v[148:151], v[128:131], v[164:167], v[148:151]
	v_mfma_f32_16x16x32_bf16 v[108:111], v[116:119], v[172:175], v[108:111]
	v_mfma_f32_16x16x32_bf16 v[104:107], v[128:131], v[172:175], v[104:107]
	v_mfma_f32_16x16x32_bf16 v[92:95], v[116:119], v[180:183], v[92:95]
	v_mfma_f32_16x16x32_bf16 v[88:91], v[128:131], v[180:183], v[88:91]
	v_mfma_f32_16x16x32_bf16 v[76:79], v[116:119], v[204:207], v[76:79]
	v_mfma_f32_16x16x32_bf16 v[72:75], v[128:131], v[204:207], v[72:75]
	s_setprio 0
	s_setprio 1
	v_mfma_f32_16x16x32_bf16 v[132:135], v[136:139], v[160:163], v[132:135]
	v_mfma_f32_16x16x32_bf16 v[124:127], v[144:147], v[160:163], v[124:127]
	v_mfma_f32_16x16x32_bf16 v[100:103], v[136:139], v[168:171], v[100:103]
	v_mfma_f32_16x16x32_bf16 v[96:99], v[144:147], v[168:171], v[96:99]
	v_mfma_f32_16x16x32_bf16 v[84:87], v[136:139], v[176:179], v[84:87]
	v_mfma_f32_16x16x32_bf16 v[80:83], v[144:147], v[176:179], v[80:83]
	v_mfma_f32_16x16x32_bf16 v[68:71], v[136:139], v[184:187], v[68:71]
	v_mfma_f32_16x16x32_bf16 v[64:67], v[144:147], v[184:187], v[64:67]
	v_mfma_f32_16x16x32_bf16 v[132:135], v[140:143], v[164:167], v[132:135]
	v_mfma_f32_16x16x32_bf16 v[124:127], v[156:159], v[164:167], v[124:127]
	v_mfma_f32_16x16x32_bf16 v[100:103], v[140:143], v[172:175], v[100:103]
	v_mfma_f32_16x16x32_bf16 v[96:99], v[156:159], v[172:175], v[96:99]
	v_mfma_f32_16x16x32_bf16 v[84:87], v[140:143], v[180:183], v[84:87]
	v_mfma_f32_16x16x32_bf16 v[80:83], v[156:159], v[180:183], v[80:83]
	v_mfma_f32_16x16x32_bf16 v[68:71], v[140:143], v[204:207], v[68:71]
	v_mfma_f32_16x16x32_bf16 v[64:67], v[156:159], v[204:207], v[64:67]
	s_setprio 0
	s_barrier
	s_add_i32 s57, s57, s28
	v_lshl_add_u64 v[208:209], s[18:19], 0, v[200:201]
	s_mov_b32 m0, s57
	ds_read_b128 v[160:163], v226 offset:16384
	ds_read_b128 v[164:167], v226 offset:17408
	ds_read_b128 v[168:171], v226 offset:18432
	ds_read_b128 v[172:175], v226 offset:19456
	ds_read_b128 v[176:179], v226 offset:20480
	ds_read_b128 v[180:183], v226 offset:21504
	ds_read_b128 v[184:187], v226 offset:22528
	ds_read_b128 v[204:207], v226 offset:23552
	global_load_lds_dwordx4 v[208:209], off
	s_add_i32 m0, s57, 0x2000
	s_add_u32 s70, s18, 0x80000
	v_lshl_add_u64 v[210:211], s[18:19], 0, v[192:193]
	s_addc_u32 s71, s19, 0
	s_add_i32 s57, s72, s28
	global_load_lds_dwordx4 v[210:211], off
	s_mov_b32 m0, s57
	v_lshl_add_u64 v[214:215], s[20:21], 0, v[190:191]
	global_load_lds_dwordx4 v200, s[70:71]
	s_add_i32 m0, s57, 0x2000
	s_nop 0
	global_load_lds_dwordx4 v192, s[70:71]
	v_lshl_add_u64 v[212:213], s[20:21], 0, v[188:189]
	s_mov_b32 m0, s29
	s_nop 0
	global_load_lds_dwordx4 v[212:213], off
	s_mov_b32 m0, s30
	s_nop 0
	global_load_lds_dwordx4 v[214:215], off
	s_waitcnt vmcnt(8)
	s_waitcnt lgkmcnt(0)
	s_barrier
; #define PG8_STAGE(bufoff, gbase, voff) do { _Pragma("unroll") for (int _i = 0; _i < 2; ++_i) \
;         __builtin_amdgcn_global_load_lds((const unsigned*)((const char*)(gbase) + (voff)[_i]), (LAS unsigned*)(lds + (bufoff) + ldsw + _i * 8192), 16, 0, 0); } while (0)
; #define PG8_LDA(dst, b, h) do { _Pragma("unroll") for (int m = 0; m < 4; ++m) _Pragma("unroll") for (int k = 0; k < 2; ++k) dst[m][k] = *(const LAS bf16x8*)(lds + PG8_SA(b, h) + aoff + m * 2048 + k * 1024); } while (0)
; #define PG8_LDB(dst, b, h) do { _Pragma("unroll") for (int n = 0; n < 2; ++n) _Pragma("unroll") for (int k = 0; k < 2; ++k) dst[n][k] = *(const LAS bf16x8*)(lds + PG8_SB(b, h) + boff + n * 2048 + k * 1024); } while (0)
; #define PG8_MMA(ai, bj, At, Bt) do { __builtin_amdgcn_s_setprio(1); _Pragma("unroll") for (int m = 0; m < 4; ++m) _Pragma("unroll") for (int n = 0; n < 2; ++n) _Pragma("unroll") for (int k = 0; k < 2; ++k) \
;         acc[ai][bj][m][n] = __builtin_amdgcn_mfma_f32_16x16x32_bf16(Bt[n][k], At[m][k], acc[ai][bj][m][n], 0, 0, 0); __builtin_amdgcn_s_setprio(0); } while (0)
; #define PG8_WAIT_V(n) asm volatile("s_waitcnt vmcnt(" #n ")" ::: "memory")
; #define PG8_WAIT_L(n) asm volatile("s_waitcnt lgkmcnt(" #n ")" ::: "memory")
; #define PG8_BAR __builtin_amdgcn_s_barrier()
; #define PG8_SCHED __builtin_amdgcn_sched_barrier(0)
; template <class Epi, class Sched, bool APERM = false, bool HALFN = false>
; __device__ __forceinline__ void gemm_phase(LAS unsigned char* lds, const int tid_in, const int K, const Sched& S, const Epi& E) {
;     ...
;             PG8_WAIT_V(8); PG8_WAIT_L(0); PG8_BAR; PG8_MMA(1, 0, At, B0); if constexpr (!HALFN) PG8_MMA(1, 1, At, B1); PG8_BAR; PG8_SCHED;
;             PG8_LDB(B0, 1, 0); PG8_LDB(B1, 1, 1); PG8_SCHED; PG8_LDA(At, 1, 0); PG8_STAGE(PG8_SA(0, 1), a2 + hstepA, voffA);
;             PG8_WAIT_V(8); PG8_WAIT_L(0); PG8_BAR; PG8_MMA(0, 0, At, B0); if constexpr (!HALFN) PG8_MMA(0, 1, At, B1); PG8_BAR; PG8_SCHED;
	s_setprio 1
	s_waitcnt lgkmcnt(0)
	v_mfma_f32_16x16x32_bf16 v[60:63], v[112:115], v[160:163], v[60:63]
	v_mfma_f32_16x16x32_bf16 v[56:59], v[120:123], v[160:163], v[56:59]
	v_mfma_f32_16x16x32_bf16 v[44:47], v[112:115], v[168:171], v[44:47]
	v_mfma_f32_16x16x32_bf16 v[40:43], v[120:123], v[168:171], v[40:43]
	v_mfma_f32_16x16x32_bf16 v[28:31], v[112:115], v[176:179], v[28:31]
	v_mfma_f32_16x16x32_bf16 v[24:27], v[120:123], v[176:179], v[24:27]
	v_mfma_f32_16x16x32_bf16 v[12:15], v[112:115], v[184:187], v[12:15]
	v_mfma_f32_16x16x32_bf16 v[8:11], v[120:123], v[184:187], v[8:11]
	v_mfma_f32_16x16x32_bf16 v[60:63], v[116:119], v[164:167], v[60:63]
	v_mfma_f32_16x16x32_bf16 v[56:59], v[128:131], v[164:167], v[56:59]
	v_mfma_f32_16x16x32_bf16 v[44:47], v[116:119], v[172:175], v[44:47]
	v_mfma_f32_16x16x32_bf16 v[40:43], v[128:131], v[172:175], v[40:43]
	v_mfma_f32_16x16x32_bf16 v[28:31], v[116:119], v[180:183], v[28:31]
	v_mfma_f32_16x16x32_bf16 v[24:27], v[128:131], v[180:183], v[24:27]
	v_mfma_f32_16x16x32_bf16 v[12:15], v[116:119], v[204:207], v[12:15]
	v_mfma_f32_16x16x32_bf16 v[8:11], v[128:131], v[204:207], v[8:11]
	s_setprio 0
	s_setprio 1
	v_mfma_f32_16x16x32_bf16 v[52:55], v[136:139], v[160:163], v[52:55]
	v_mfma_f32_16x16x32_bf16 v[48:51], v[144:147], v[160:163], v[48:51]
	v_mfma_f32_16x16x32_bf16 v[36:39], v[136:139], v[168:171], v[36:39]
	v_mfma_f32_16x16x32_bf16 v[32:35], v[144:147], v[168:171], v[32:35]
	v_mfma_f32_16x16x32_bf16 v[20:23], v[136:139], v[176:179], v[20:23]
	v_mfma_f32_16x16x32_bf16 v[16:19], v[144:147], v[176:179], v[16:19]
	v_mfma_f32_16x16x32_bf16 v[4:7], v[136:139], v[184:187], v[4:7]
	v_mfma_f32_16x16x32_bf16 v[0:3], v[144:147], v[184:187], v[0:3]
	v_mfma_f32_16x16x32_bf16 v[52:55], v[140:143], v[164:167], v[52:55]
	v_mfma_f32_16x16x32_bf16 v[48:51], v[156:159], v[164:167], v[48:51]
	v_mfma_f32_16x16x32_bf16 v[36:39], v[140:143], v[172:175], v[36:39]
	v_mfma_f32_16x16x32_bf16 v[32:35], v[156:159], v[172:175], v[32:35]
	v_mfma_f32_16x16x32_bf16 v[20:23], v[140:143], v[180:183], v[20:23]
	v_mfma_f32_16x16x32_bf16 v[16:19], v[156:159], v[180:183], v[16:19]
	v_mfma_f32_16x16x32_bf16 v[4:7], v[140:143], v[204:207], v[4:7]
	v_mfma_f32_16x16x32_bf16 v[0:3], v[156:159], v[204:207], v[0:3]
	s_setprio 0
	s_barrier
	s_add_i32 s57, 0, 0x18000
	s_add_i32 s70, 0, 0x1c000
	v_add_u32_e32 v128, s57, v220
	v_add_u32_e32 v156, s70, v220
	ds_read_b128 v[112:115], v128
	ds_read_b128 v[116:119], v128 offset:1024
	ds_read_b128 v[120:123], v128 offset:2048
	ds_read_b128 v[128:131], v128 offset:3072
	ds_read_b128 v[136:139], v156
	ds_read_b128 v[140:143], v156 offset:1024
	ds_read_b128 v[144:147], v156 offset:2048
	ds_read_b128 v[156:159], v156 offset:3072
	s_add_u32 s20, s20, 0x80000
	s_addc_u32 s21, s21, 0
	s_mov_b32 m0, s31
	ds_read_b128 v[160:163], v226 offset:32768
	ds_read_b128 v[164:167], v226 offset:33792
	ds_read_b128 v[168:171], v226 offset:34816
	ds_read_b128 v[172:175], v226 offset:35840
	ds_read_b128 v[176:179], v226 offset:36864
	ds_read_b128 v[180:183], v226 offset:37888
	ds_read_b128 v[184:187], v226 offset:38912
	ds_read_b128 v[204:207], v226 offset:39936
	global_load_lds_dwordx4 v188, s[20:21]
	s_mov_b32 m0, s34
	s_nop 0
	global_load_lds_dwordx4 v190, s[20:21]
	s_waitcnt vmcnt(8)
	s_waitcnt lgkmcnt(0)
	s_barrier
	s_setprio 1
	s_waitcnt lgkmcnt(0)
	v_mfma_f32_16x16x32_bf16 v[152:155], v[112:115], v[160:163], v[152:155]
	v_mfma_f32_16x16x32_bf16 v[148:151], v[120:123], v[160:163], v[148:151]
	v_mfma_f32_16x16x32_bf16 v[108:111], v[112:115], v[168:171], v[108:111]
	v_mfma_f32_16x16x32_bf16 v[104:107], v[120:123], v[168:171], v[104:107]
	v_mfma_f32_16x16x32_bf16 v[92:95], v[112:115], v[176:179], v[92:95]
	v_mfma_f32_16x16x32_bf16 v[88:91], v[120:123], v[176:179], v[88:91]
	v_mfma_f32_16x16x32_bf16 v[76:79], v[112:115], v[184:187], v[76:79]
	v_mfma_f32_16x16x32_bf16 v[72:75], v[120:123], v[184:187], v[72:75]
	v_mfma_f32_16x16x32_bf16 v[152:155], v[116:119], v[164:167], v[152:155]
	v_mfma_f32_16x16x32_bf16 v[148:151], v[128:131], v[164:167], v[148:151]
	v_mfma_f32_16x16x32_bf16 v[108:111], v[116:119], v[172:175], v[108:111]
	v_mfma_f32_16x16x32_bf16 v[104:107], v[128:131], v[172:175], v[104:107]
	v_mfma_f32_16x16x32_bf16 v[92:95], v[116:119], v[180:183], v[92:95]
	v_mfma_f32_16x16x32_bf16 v[88:91], v[128:131], v[180:183], v[88:91]
	v_mfma_f32_16x16x32_bf16 v[76:79], v[116:119], v[204:207], v[76:79]
	v_mfma_f32_16x16x32_bf16 v[72:75], v[128:131], v[204:207], v[72:75]
	s_setprio 0
	s_setprio 1
	v_mfma_f32_16x16x32_bf16 v[132:135], v[136:139], v[160:163], v[132:135]
	v_mfma_f32_16x16x32_bf16 v[124:127], v[144:147], v[160:163], v[124:127]
	v_mfma_f32_16x16x32_bf16 v[100:103], v[136:139], v[168:171], v[100:103]
	v_mfma_f32_16x16x32_bf16 v[96:99], v[144:147], v[168:171], v[96:99]
	v_mfma_f32_16x16x32_bf16 v[84:87], v[136:139], v[176:179], v[84:87]
	v_mfma_f32_16x16x32_bf16 v[80:83], v[144:147], v[176:179], v[80:83]
	v_mfma_f32_16x16x32_bf16 v[68:71], v[136:139], v[184:187], v[68:71]
	v_mfma_f32_16x16x32_bf16 v[64:67], v[144:147], v[184:187], v[64:67]
	v_mfma_f32_16x16x32_bf16 v[132:135], v[140:143], v[164:167], v[132:135]
	v_mfma_f32_16x16x32_bf16 v[124:127], v[156:159], v[164:167], v[124:127]
	v_mfma_f32_16x16x32_bf16 v[100:103], v[140:143], v[172:175], v[100:103]
	v_mfma_f32_16x16x32_bf16 v[96:99], v[156:159], v[172:175], v[96:99]
	v_mfma_f32_16x16x32_bf16 v[84:87], v[140:143], v[180:183], v[84:87]
	v_mfma_f32_16x16x32_bf16 v[80:83], v[156:159], v[180:183], v[80:83]
	v_mfma_f32_16x16x32_bf16 v[68:71], v[140:143], v[204:207], v[68:71]
	v_mfma_f32_16x16x32_bf16 v[64:67], v[156:159], v[204:207], v[64:67]
	s_setprio 0
	s_barrier
; #define PG8_STAGE(bufoff, gbase, voff) do { _Pragma("unroll") for (int _i = 0; _i < 2; ++_i) \
;         __builtin_amdgcn_global_load_lds((const unsigned*)((const char*)(gbase) + (voff)[_i]), (LAS unsigned*)(lds + (bufoff) + ldsw + _i * 8192), 16, 0, 0); } while (0)
; #define PG8_LDA(dst, b, h) do { _Pragma("unroll") for (int m = 0; m < 4; ++m) _Pragma("unroll") for (int k = 0; k < 2; ++k) dst[m][k] = *(const LAS bf16x8*)(lds + PG8_SA(b, h) + aoff + m * 2048 + k * 1024); } while (0)
; #define PG8_MMA(ai, bj, At, Bt) do { __builtin_amdgcn_s_setprio(1); _Pragma("unroll") for (int m = 0; m < 4; ++m) _Pragma("unroll") for (int n = 0; n < 2; ++n) _Pragma("unroll") for (int k = 0; k < 2; ++k) \
;         acc[ai][bj][m][n] = __builtin_amdgcn_mfma_f32_16x16x32_bf16(Bt[n][k], At[m][k], acc[ai][bj][m][n], 0, 0, 0); __builtin_amdgcn_s_setprio(0); } while (0)
; #define PG8_WAIT_V(n) asm volatile("s_waitcnt vmcnt(" #n ")" ::: "memory")
; #define PG8_WAIT_L(n) asm volatile("s_waitcnt lgkmcnt(" #n ")" ::: "memory")
; #define PG8_BAR __builtin_amdgcn_s_barrier()
; #define PG8_SCHED __builtin_amdgcn_sched_barrier(0)
; template <class Epi, class Sched, bool APERM = false, bool HALFN = false>
; __device__ __forceinline__ void gemm_phase(LAS unsigned char* lds, const int tid_in, const int K, const Sched& S, const Epi& E) {
;     ...
;             PG8_LDA(At, 1, 1); PG8_STAGE(PG8_SB(1, 0), b3, voffB); PG8_STAGE(PG8_SB(1, 1), b3 + hstep, voffB); PG8_STAGE(PG8_SA(1, 0), a3, voffA);
;             PG8_WAIT_V(8); PG8_WAIT_L(0); PG8_BAR; PG8_MMA(1, 0, At, B0); if constexpr (!HALFN) PG8_MMA(1, 1, At, B1); PG8_BAR; PG8_SCHED;
;         }
;         if (wr == 0) PG8_BAR;
	s_add_i32 s20, s57, s28
	v_lshl_add_u64 v[208:209], v[208:209], 0, s[78:79]
	s_mov_b32 m0, s20
	ds_read_b128 v[160:163], v226 offset:49152
	ds_read_b128 v[164:167], v226 offset:50176
	ds_read_b128 v[168:171], v226 offset:51200
	ds_read_b128 v[172:175], v226 offset:52224
	ds_read_b128 v[176:179], v226 offset:53248
	ds_read_b128 v[180:183], v226 offset:54272
	ds_read_b128 v[184:187], v226 offset:55296
	ds_read_b128 v[204:207], v226 offset:56320
	global_load_lds_dwordx4 v[208:209], off
	s_add_i32 m0, s20, 0x2000
	s_add_u32 s18, s18, 0x80080
	v_lshl_add_u64 v[208:209], v[210:211], 0, s[78:79]
	s_addc_u32 s19, s19, 0
	s_add_i32 s20, s70, s28
	global_load_lds_dwordx4 v[208:209], off
	s_mov_b32 m0, s20
	s_nop 0
	global_load_lds_dwordx4 v200, s[18:19]
	s_add_i32 m0, s20, 0x2000
	s_nop 0
	global_load_lds_dwordx4 v192, s[18:19]
	v_lshl_add_u64 v[208:209], v[212:213], 0, s[78:79]
	s_mov_b32 m0, s35
	s_nop 0
	global_load_lds_dwordx4 v[208:209], off
	v_lshl_add_u64 v[208:209], v[214:215], 0, s[78:79]
	s_mov_b32 m0, s38
	s_nop 0
	global_load_lds_dwordx4 v[208:209], off
	s_waitcnt vmcnt(8)
	s_waitcnt lgkmcnt(0)
	s_barrier
	s_setprio 1
	s_waitcnt lgkmcnt(0)
	v_mfma_f32_16x16x32_bf16 v[60:63], v[112:115], v[160:163], v[60:63]
	v_mfma_f32_16x16x32_bf16 v[56:59], v[120:123], v[160:163], v[56:59]
	v_mfma_f32_16x16x32_bf16 v[44:47], v[112:115], v[168:171], v[44:47]
	v_mfma_f32_16x16x32_bf16 v[40:43], v[120:123], v[168:171], v[40:43]
	v_mfma_f32_16x16x32_bf16 v[28:31], v[112:115], v[176:179], v[28:31]
	v_mfma_f32_16x16x32_bf16 v[24:27], v[120:123], v[176:179], v[24:27]
	v_mfma_f32_16x16x32_bf16 v[12:15], v[112:115], v[184:187], v[12:15]
	v_mfma_f32_16x16x32_bf16 v[8:11], v[120:123], v[184:187], v[8:11]
	v_mfma_f32_16x16x32_bf16 v[60:63], v[116:119], v[164:167], v[60:63]
	v_mfma_f32_16x16x32_bf16 v[56:59], v[128:131], v[164:167], v[56:59]
	v_mfma_f32_16x16x32_bf16 v[44:47], v[116:119], v[172:175], v[44:47]
	v_mfma_f32_16x16x32_bf16 v[40:43], v[128:131], v[172:175], v[40:43]
	v_mfma_f32_16x16x32_bf16 v[28:31], v[116:119], v[180:183], v[28:31]
	v_mfma_f32_16x16x32_bf16 v[24:27], v[128:131], v[180:183], v[24:27]
	v_mfma_f32_16x16x32_bf16 v[12:15], v[116:119], v[204:207], v[12:15]
	v_mfma_f32_16x16x32_bf16 v[8:11], v[128:131], v[204:207], v[8:11]
	s_setprio 0
	s_setprio 1
	v_mfma_f32_16x16x32_bf16 v[52:55], v[136:139], v[160:163], v[52:55]
	v_mfma_f32_16x16x32_bf16 v[48:51], v[144:147], v[160:163], v[48:51]
	v_mfma_f32_16x16x32_bf16 v[36:39], v[136:139], v[168:171], v[36:39]
	v_mfma_f32_16x16x32_bf16 v[32:35], v[144:147], v[168:171], v[32:35]
	v_mfma_f32_16x16x32_bf16 v[20:23], v[136:139], v[176:179], v[20:23]
	v_mfma_f32_16x16x32_bf16 v[16:19], v[144:147], v[176:179], v[16:19]
	v_mfma_f32_16x16x32_bf16 v[4:7], v[136:139], v[184:187], v[4:7]
	v_mfma_f32_16x16x32_bf16 v[0:3], v[144:147], v[184:187], v[0:3]
	v_mfma_f32_16x16x32_bf16 v[52:55], v[140:143], v[164:167], v[52:55]
	v_mfma_f32_16x16x32_bf16 v[48:51], v[156:159], v[164:167], v[48:51]
	v_mfma_f32_16x16x32_bf16 v[36:39], v[140:143], v[172:175], v[36:39]
	v_mfma_f32_16x16x32_bf16 v[32:35], v[156:159], v[172:175], v[32:35]
	v_mfma_f32_16x16x32_bf16 v[20:23], v[140:143], v[180:183], v[20:23]
	v_mfma_f32_16x16x32_bf16 v[16:19], v[156:159], v[180:183], v[16:19]
	v_mfma_f32_16x16x32_bf16 v[4:7], v[140:143], v[204:207], v[4:7]
	v_mfma_f32_16x16x32_bf16 v[0:3], v[156:159], v[204:207], v[0:3]
	s_setprio 0
	s_barrier
	s_add_i32 s53, s53, 2
	s_add_u32 s45, s45, 0x100
	s_addc_u32 s52, s52, 0
	s_add_u32 s16, s16, 0x100
	s_addc_u32 s17, s17, 0
	s_cmp_gt_u32 s53, 29
	s_cbranch_scc0 .LBB0_682
	s_and_b64 vcc, exec, s[8:9]
	s_cbranch_vccz .LBB0_685
	s_barrier

; #define PG8_STAGE(bufoff, gbase, voff) do { _Pragma("unroll") for (int _i = 0; _i < 2; ++_i) \
;         __builtin_amdgcn_global_load_lds((const unsigned*)((const char*)(gbase) + (voff)[_i]), (LAS unsigned*)(lds + (bufoff) + ldsw + _i * 8192), 16, 0, 0); } while (0)
; #define PG8_LDA(dst, b, h) do { _Pragma("unroll") for (int m = 0; m < 4; ++m) _Pragma("unroll") for (int k = 0; k < 2; ++k) dst[m][k] = *(const LAS bf16x8*)(lds + PG8_SA(b, h) + aoff + m * 2048 + k * 1024); } while (0)
; #define PG8_LDB(dst, b, h) do { _Pragma("unroll") for (int n = 0; n < 2; ++n) _Pragma("unroll") for (int k = 0; k < 2; ++k) dst[n][k] = *(const LAS bf16x8*)(lds + PG8_SB(b, h) + boff + n * 2048 + k * 1024); } while (0)
; #define PG8_WAIT_V(n) asm volatile("s_waitcnt vmcnt(" #n ")" ::: "memory")
; #define PG8_BAR __builtin_amdgcn_s_barrier()
; template <class Epi, class Sched, bool APERM = false, bool HALFN = false>
; __device__ __forceinline__ void gemm_phase(LAS unsigned char* lds, const int tid_in, const int K, const Sched& S, const Epi& E) {
;     ...
;     for (;;) {
;         const bool has_next = S.next(ui + 1, nxt);
;         const char* nA = has_next ? nxt.A : cA; const char* nB = has_next ? nxt.B : cB;
;         for (int t = 0; t < nt; t += 2) {
;             const bool last = (t == nt - 2);
;             const char* a1 = cA + (size_t)(t + 1) * kstep;
;             const char* a2 = last ? nA : cA + (size_t)(t + 2) * kstep; const char* b2 = last ? nB : cB + (size_t)(t + 2) * kstep;
;             const char* a3 = a2 + kstep; const char* b3 = b2 + kstep;
;             PG8_LDB(B0, 0, 0); PG8_LDB(B1, 0, 1); PG8_SCHED; PG8_LDA(At, 0, 0); PG8_STAGE(PG8_SA(1, 1), a1 + hstepA, voffA);
;             PG8_WAIT_V(8); PG8_WAIT_L(0); PG8_BAR; PG8_MMA(0, 0, At, B0); if constexpr (!HALFN) PG8_MMA(0, 1, At, B1); PG8_BAR; PG8_SCHED;
;             PG8_LDA(At, 0, 1); PG8_STAGE(PG8_SB(0, 0), b2, voffB); PG8_STAGE(PG8_SB(0, 1), b2 + hstep, voffB); PG8_STAGE(PG8_SA(0, 0), a2, voffA);
;             PG8_WAIT_V(8); PG8_WAIT_L(0); PG8_BAR; PG8_MMA(1, 0, At, B0); if constexpr (!HALFN) PG8_MMA(1, 1, At, B1); PG8_BAR; PG8_SCHED;
;             PG8_LDB(B0, 1, 0); PG8_LDB(B1, 1, 1); PG8_SCHED; PG8_LDA(At, 1, 0); PG8_STAGE(PG8_SA(0, 1), a2 + hstepA, voffA);
;             PG8_WAIT_V(8); PG8_WAIT_L(0); PG8_BAR; PG8_MMA(0, 0, At, B0); if constexpr (!HALFN) PG8_MMA(0, 1, At, B1); PG8_BAR; PG8_SCHED;
.LBB0_766:
	s_add_u32 s20, s18, 0xfff80080
	s_addc_u32 s21, s19, -1
	s_add_i32 s87, 0, 0x10000
	v_add_u32_e32 v95, s87, v99
	ds_read_b128 v[102:105], v95
	ds_read_b128 v[106:109], v95 offset:1024
	ds_read_b128 v[110:113], v95 offset:2048
	ds_read_b128 v[114:117], v95 offset:3072
	v_readlane_b32 s22, v255, 56
	s_nop 1
	s_cmp_eq_u32 s86, s22
	s_cselect_b32 s23, s76, s21
	s_cselect_b32 s22, s77, s20
	s_cselect_b32 s21, s74, s81
	s_cselect_b32 s20, s75, s80
	s_add_i32 m0, s34, 0xc000
	ds_read_b128 v[118:121], v101
	ds_read_b128 v[122:125], v101 offset:1024
	ds_read_b128 v[126:129], v101 offset:2048
	ds_read_b128 v[130:133], v101 offset:3072
	ds_read_b128 v[134:137], v101 offset:4096
	ds_read_b128 v[138:141], v101 offset:5120
	ds_read_b128 v[142:145], v101 offset:6144
	ds_read_b128 v[148:151], v101 offset:7168
	global_load_lds_dwordx4 v92, s[18:19]
	s_add_i32 m0, s34, 0xe000
	s_nop 0
	global_load_lds_dwordx4 v90, s[18:19]
	s_waitcnt vmcnt(8)
	s_waitcnt lgkmcnt(0)
	s_barrier
	s_setprio 1
	s_waitcnt lgkmcnt(0)
	v_mfma_f32_16x16x32_bf16 v[60:63], v[102:105], v[118:121], v[60:63]
	v_mfma_f32_16x16x32_bf16 v[56:59], v[110:113], v[118:121], v[56:59]
	v_mfma_f32_16x16x32_bf16 v[52:55], v[102:105], v[126:129], v[52:55]
	v_mfma_f32_16x16x32_bf16 v[48:51], v[110:113], v[126:129], v[48:51]
	v_mfma_f32_16x16x32_bf16 v[44:47], v[102:105], v[134:137], v[44:47]
	v_mfma_f32_16x16x32_bf16 v[40:43], v[110:113], v[134:137], v[40:43]
	v_mfma_f32_16x16x32_bf16 v[36:39], v[102:105], v[142:145], v[36:39]
	v_mfma_f32_16x16x32_bf16 v[32:35], v[110:113], v[142:145], v[32:35]
	v_mfma_f32_16x16x32_bf16 v[60:63], v[106:109], v[122:125], v[60:63]
	v_mfma_f32_16x16x32_bf16 v[56:59], v[114:117], v[122:125], v[56:59]
	v_mfma_f32_16x16x32_bf16 v[52:55], v[106:109], v[130:133], v[52:55]
	v_mfma_f32_16x16x32_bf16 v[48:51], v[114:117], v[130:133], v[48:51]
	v_mfma_f32_16x16x32_bf16 v[44:47], v[106:109], v[138:141], v[44:47]
	v_mfma_f32_16x16x32_bf16 v[40:43], v[114:117], v[138:141], v[40:43]
	v_mfma_f32_16x16x32_bf16 v[36:39], v[106:109], v[148:151], v[36:39]
	v_mfma_f32_16x16x32_bf16 v[32:35], v[114:117], v[148:151], v[32:35]
	s_setprio 0
	s_barrier
	s_add_i32 s87, s87, s27
	v_lshl_add_u64 v[96:97], s[20:21], 0, v[68:69]
	s_mov_b32 m0, s87
	ds_read_b128 v[118:121], v101 offset:16384
	ds_read_b128 v[122:125], v101 offset:17408
	ds_read_b128 v[126:129], v101 offset:18432
	ds_read_b128 v[130:133], v101 offset:19456
	ds_read_b128 v[134:137], v101 offset:20480
	ds_read_b128 v[138:141], v101 offset:21504
	ds_read_b128 v[142:145], v101 offset:22528
	ds_read_b128 v[148:151], v101 offset:23552
	global_load_lds_dwordx4 v[96:97], off
	s_add_i32 m0, s87, 0x2000
	s_add_u32 s92, s20, 0x80000
	v_lshl_add_u64 v[152:153], s[20:21], 0, v[64:65]
	s_addc_u32 s93, s21, 0
	global_load_lds_dwordx4 v[152:153], off
	s_mov_b32 m0, s35
	v_lshl_add_u64 v[156:157], s[22:23], 0, v[66:67]
	global_load_lds_dwordx4 v68, s[92:93]
	s_mov_b32 m0, s38
	s_nop 0
	global_load_lds_dwordx4 v64, s[92:93]
	v_lshl_add_u64 v[154:155], s[22:23], 0, v[70:71]
	s_mov_b32 m0, s34
	s_nop 0
	global_load_lds_dwordx4 v[154:155], off
	s_mov_b32 m0, s39
	s_nop 0
	global_load_lds_dwordx4 v[156:157], off
	s_waitcnt vmcnt(8)
	s_waitcnt lgkmcnt(0)
	s_barrier
	s_setprio 1
	s_waitcnt lgkmcnt(0)
	v_mfma_f32_16x16x32_bf16 v[28:31], v[102:105], v[118:121], v[28:31]
	v_mfma_f32_16x16x32_bf16 v[24:27], v[110:113], v[118:121], v[24:27]
	v_mfma_f32_16x16x32_bf16 v[20:23], v[102:105], v[126:129], v[20:23]
	v_mfma_f32_16x16x32_bf16 v[16:19], v[110:113], v[126:129], v[16:19]
	v_mfma_f32_16x16x32_bf16 v[12:15], v[102:105], v[134:137], v[12:15]
	v_mfma_f32_16x16x32_bf16 v[8:11], v[110:113], v[134:137], v[8:11]
	v_mfma_f32_16x16x32_bf16 v[4:7], v[102:105], v[142:145], v[4:7]
	v_mfma_f32_16x16x32_bf16 v[0:3], v[110:113], v[142:145], v[0:3]
	v_mfma_f32_16x16x32_bf16 v[28:31], v[106:109], v[122:125], v[28:31]
	v_mfma_f32_16x16x32_bf16 v[24:27], v[114:117], v[122:125], v[24:27]
	v_mfma_f32_16x16x32_bf16 v[20:23], v[106:109], v[130:133], v[20:23]
	v_mfma_f32_16x16x32_bf16 v[16:19], v[114:117], v[130:133], v[16:19]
	v_mfma_f32_16x16x32_bf16 v[12:15], v[106:109], v[138:141], v[12:15]
	v_mfma_f32_16x16x32_bf16 v[8:11], v[114:117], v[138:141], v[8:11]
	v_mfma_f32_16x16x32_bf16 v[4:7], v[106:109], v[148:151], v[4:7]
	v_mfma_f32_16x16x32_bf16 v[0:3], v[114:117], v[148:151], v[0:3]
	s_setprio 0
	s_barrier
; #define PG8_STAGE(bufoff, gbase, voff) do { _Pragma("unroll") for (int _i = 0; _i < 2; ++_i) \
;         __builtin_amdgcn_global_load_lds((const unsigned*)((const char*)(gbase) + (voff)[_i]), (LAS unsigned*)(lds + (bufoff) + ldsw + _i * 8192), 16, 0, 0); } while (0)
; #define PG8_LDA(dst, b, h) do { _Pragma("unroll") for (int m = 0; m < 4; ++m) _Pragma("unroll") for (int k = 0; k < 2; ++k) dst[m][k] = *(const LAS bf16x8*)(lds + PG8_SA(b, h) + aoff + m * 2048 + k * 1024); } while (0)
; #define PG8_LDB(dst, b, h) do { _Pragma("unroll") for (int n = 0; n < 2; ++n) _Pragma("unroll") for (int k = 0; k < 2; ++k) dst[n][k] = *(const LAS bf16x8*)(lds + PG8_SB(b, h) + boff + n * 2048 + k * 1024); } while (0)
; #define PG8_MMA(ai, bj, At, Bt) do { __builtin_amdgcn_s_setprio(1); _Pragma("unroll") for (int m = 0; m < 4; ++m) _Pragma("unroll") for (int n = 0; n < 2; ++n) _Pragma("unroll") for (int k = 0; k < 2; ++k) \
;         acc[ai][bj][m][n] = __builtin_amdgcn_mfma_f32_16x16x32_bf16(Bt[n][k], At[m][k], acc[ai][bj][m][n], 0, 0, 0); __builtin_amdgcn_s_setprio(0); } while (0)
; #define PG8_WAIT_V(n) asm volatile("s_waitcnt vmcnt(" #n ")" ::: "memory")
; #define PG8_WAIT_L(n) asm volatile("s_waitcnt lgkmcnt(" #n ")" ::: "memory")
; #define PG8_BAR __builtin_amdgcn_s_barrier()
; #define PG8_SCHED __builtin_amdgcn_sched_barrier(0)
; template <class Epi, class Sched, bool APERM = false, bool HALFN = false>
; __device__ __forceinline__ void gemm_phase(LAS unsigned char* lds, const int tid_in, const int K, const Sched& S, const Epi& E) {
;     ...
;             PG8_LDB(B0, 1, 0); PG8_LDB(B1, 1, 1); PG8_SCHED; PG8_LDA(At, 1, 0); PG8_STAGE(PG8_SA(0, 1), a2 + hstepA, voffA);
;             PG8_WAIT_V(8); PG8_WAIT_L(0); PG8_BAR; PG8_MMA(0, 0, At, B0); if constexpr (!HALFN) PG8_MMA(0, 1, At, B1); PG8_BAR; PG8_SCHED;
;             PG8_LDA(At, 1, 1); PG8_STAGE(PG8_SB(1, 0), b3, voffB); PG8_STAGE(PG8_SB(1, 1), b3 + hstep, voffB); PG8_STAGE(PG8_SA(1, 0), a3, voffA);
;             PG8_WAIT_V(8); PG8_WAIT_L(0); PG8_BAR; PG8_MMA(1, 0, At, B0); if constexpr (!HALFN) PG8_MMA(1, 1, At, B1); PG8_BAR; PG8_SCHED;
;         }
;         if (wr == 0) PG8_BAR;
	s_add_i32 s87, 0, 0x18000
	v_add_u32_e32 v95, s87, v99
	ds_read_b128 v[102:105], v95
	ds_read_b128 v[106:109], v95 offset:1024
	ds_read_b128 v[110:113], v95 offset:2048
	ds_read_b128 v[114:117], v95 offset:3072
	s_add_u32 s22, s22, 0x80000
	s_addc_u32 s23, s23, 0
	s_mov_b32 m0, s44
	ds_read_b128 v[118:121], v101 offset:32768
	ds_read_b128 v[122:125], v101 offset:33792
	ds_read_b128 v[126:129], v101 offset:34816
	ds_read_b128 v[130:133], v101 offset:35840
	ds_read_b128 v[134:137], v101 offset:36864
	ds_read_b128 v[138:141], v101 offset:37888
	ds_read_b128 v[142:145], v101 offset:38912
	ds_read_b128 v[148:151], v101 offset:39936
	global_load_lds_dwordx4 v70, s[22:23]
	s_mov_b32 m0, s45
	s_nop 0
	global_load_lds_dwordx4 v66, s[22:23]
	s_waitcnt vmcnt(8)
	s_waitcnt lgkmcnt(0)
	s_barrier
	s_setprio 1
	s_waitcnt lgkmcnt(0)
	v_mfma_f32_16x16x32_bf16 v[60:63], v[102:105], v[118:121], v[60:63]
	v_mfma_f32_16x16x32_bf16 v[56:59], v[110:113], v[118:121], v[56:59]
	v_mfma_f32_16x16x32_bf16 v[52:55], v[102:105], v[126:129], v[52:55]
	v_mfma_f32_16x16x32_bf16 v[48:51], v[110:113], v[126:129], v[48:51]
	v_mfma_f32_16x16x32_bf16 v[44:47], v[102:105], v[134:137], v[44:47]
	v_mfma_f32_16x16x32_bf16 v[40:43], v[110:113], v[134:137], v[40:43]
	v_mfma_f32_16x16x32_bf16 v[36:39], v[102:105], v[142:145], v[36:39]
	v_mfma_f32_16x16x32_bf16 v[32:35], v[110:113], v[142:145], v[32:35]
	v_mfma_f32_16x16x32_bf16 v[60:63], v[106:109], v[122:125], v[60:63]
	v_mfma_f32_16x16x32_bf16 v[56:59], v[114:117], v[122:125], v[56:59]
	v_mfma_f32_16x16x32_bf16 v[52:55], v[106:109], v[130:133], v[52:55]
	v_mfma_f32_16x16x32_bf16 v[48:51], v[114:117], v[130:133], v[48:51]
	v_mfma_f32_16x16x32_bf16 v[44:47], v[106:109], v[138:141], v[44:47]
	v_mfma_f32_16x16x32_bf16 v[40:43], v[114:117], v[138:141], v[40:43]
	v_mfma_f32_16x16x32_bf16 v[36:39], v[106:109], v[148:151], v[36:39]
	v_mfma_f32_16x16x32_bf16 v[32:35], v[114:117], v[148:151], v[32:35]
	s_setprio 0
	s_barrier
	s_add_i32 s22, s87, s27
	v_lshl_add_u64 v[96:97], v[96:97], 0, s[78:79]
	s_mov_b32 m0, s22
	ds_read_b128 v[118:121], v101 offset:49152
	ds_read_b128 v[122:125], v101 offset:50176
	ds_read_b128 v[126:129], v101 offset:51200
	ds_read_b128 v[130:133], v101 offset:52224
	ds_read_b128 v[134:137], v101 offset:53248
	ds_read_b128 v[138:141], v101 offset:54272
	ds_read_b128 v[142:145], v101 offset:55296
	ds_read_b128 v[148:151], v101 offset:56320
	global_load_lds_dwordx4 v[96:97], off
	s_add_i32 m0, s22, 0x2000
	s_add_u32 s20, s20, 0x80080
	v_lshl_add_u64 v[96:97], v[152:153], 0, s[78:79]
	s_addc_u32 s21, s21, 0
	global_load_lds_dwordx4 v[96:97], off
	s_mov_b32 m0, s57
	s_nop 0
	global_load_lds_dwordx4 v68, s[20:21]
	s_mov_b32 m0, s70
	s_nop 0
	global_load_lds_dwordx4 v64, s[20:21]
	v_lshl_add_u64 v[96:97], v[154:155], 0, s[78:79]
	s_mov_b32 m0, s52
	s_nop 0
	global_load_lds_dwordx4 v[96:97], off
	v_lshl_add_u64 v[96:97], v[156:157], 0, s[78:79]
	s_mov_b32 m0, s53
	s_nop 0
	global_load_lds_dwordx4 v[96:97], off
	s_waitcnt vmcnt(8)
	s_waitcnt lgkmcnt(0)
	s_barrier
	s_setprio 1
	s_waitcnt lgkmcnt(0)
	v_mfma_f32_16x16x32_bf16 v[28:31], v[102:105], v[118:121], v[28:31]
	v_mfma_f32_16x16x32_bf16 v[24:27], v[110:113], v[118:121], v[24:27]
	v_mfma_f32_16x16x32_bf16 v[20:23], v[102:105], v[126:129], v[20:23]
	v_mfma_f32_16x16x32_bf16 v[16:19], v[110:113], v[126:129], v[16:19]
	v_mfma_f32_16x16x32_bf16 v[12:15], v[102:105], v[134:137], v[12:15]
	v_mfma_f32_16x16x32_bf16 v[8:11], v[110:113], v[134:137], v[8:11]
	v_mfma_f32_16x16x32_bf16 v[4:7], v[102:105], v[142:145], v[4:7]
	v_mfma_f32_16x16x32_bf16 v[0:3], v[110:113], v[142:145], v[0:3]
	v_mfma_f32_16x16x32_bf16 v[28:31], v[106:109], v[122:125], v[28:31]
	v_mfma_f32_16x16x32_bf16 v[24:27], v[114:117], v[122:125], v[24:27]
	v_mfma_f32_16x16x32_bf16 v[20:23], v[106:109], v[130:133], v[20:23]
	v_mfma_f32_16x16x32_bf16 v[16:19], v[114:117], v[130:133], v[16:19]
	v_mfma_f32_16x16x32_bf16 v[12:15], v[106:109], v[138:141], v[12:15]
	v_mfma_f32_16x16x32_bf16 v[8:11], v[114:117], v[138:141], v[8:11]
	v_mfma_f32_16x16x32_bf16 v[4:7], v[106:109], v[148:151], v[4:7]
	v_mfma_f32_16x16x32_bf16 v[0:3], v[114:117], v[148:151], v[0:3]
	s_setprio 0
	s_barrier
	s_add_i32 s86, s86, 2
	s_add_u32 s80, s80, 0x100
	s_addc_u32 s81, s81, 0
	s_add_u32 s18, s18, 0x100
	s_addc_u32 s19, s19, 0
	v_readlane_b32 s20, v255, 55
	s_nop 1
	s_cmp_gt_u32 s86, s20
	s_cbranch_scc0 .LBB0_766
	s_and_b64 vcc, exec, s[12:13]
	s_cbranch_vccz .LBB0_769
	s_barrier

; #define PG8_STAGE(bufoff, gbase, voff) do { _Pragma("unroll") for (int _i = 0; _i < 2; ++_i) \
;         __builtin_amdgcn_global_load_lds((const unsigned*)((const char*)(gbase) + (voff)[_i]), (LAS unsigned*)(lds + (bufoff) + ldsw + _i * 8192), 16, 0, 0); } while (0)
; #define PG8_LDA(dst, b, h) do { _Pragma("unroll") for (int m = 0; m < 4; ++m) _Pragma("unroll") for (int k = 0; k < 2; ++k) dst[m][k] = *(const LAS bf16x8*)(lds + PG8_SA(b, h) + aoff + m * 2048 + k * 1024); } while (0)
; #define PG8_LDB(dst, b, h) do { _Pragma("unroll") for (int n = 0; n < 2; ++n) _Pragma("unroll") for (int k = 0; k < 2; ++k) dst[n][k] = *(const LAS bf16x8*)(lds + PG8_SB(b, h) + boff + n * 2048 + k * 1024); } while (0)
; #define PG8_MMA(ai, bj, At, Bt) do { __builtin_amdgcn_s_setprio(1); _Pragma("unroll") for (int m = 0; m < 4; ++m) _Pragma("unroll") for (int n = 0; n < 2; ++n) _Pragma("unroll") for (int k = 0; k < 2; ++k) \
;         acc[ai][bj][m][n] = __builtin_amdgcn_mfma_f32_16x16x32_bf16(Bt[n][k], At[m][k], acc[ai][bj][m][n], 0, 0, 0); __builtin_amdgcn_s_setprio(0); } while (0)
; #define PG8_WAIT_V(n) asm volatile("s_waitcnt vmcnt(" #n ")" ::: "memory")
; #define PG8_WAIT_L(n) asm volatile("s_waitcnt lgkmcnt(" #n ")" ::: "memory")
; template <class Epi, class Sched, bool APERM = false, bool HALFN = false>
; __device__ __forceinline__ void gemm_phase(LAS unsigned char* lds, const int tid_in, const int K, const Sched& S, const Epi& E) {
;     ...
;     for (;;) {
;         const bool has_next = S.next(ui + 1, nxt);
;         const char* nA = has_next ? nxt.A : cA; const char* nB = has_next ? nxt.B : cB;
;         for (int t = 0; t < nt; t += 2) {
;             const bool last = (t == nt - 2);
;             const char* a1 = cA + (size_t)(t + 1) * kstep;
;             const char* a2 = last ? nA : cA + (size_t)(t + 2) * kstep; const char* b2 = last ? nB : cB + (size_t)(t + 2) * kstep;
;             const char* a3 = a2 + kstep; const char* b3 = b2 + kstep;
;             PG8_LDB(B0, 0, 0); PG8_LDB(B1, 0, 1); PG8_SCHED; PG8_LDA(At, 0, 0); PG8_STAGE(PG8_SA(1, 1), a1 + hstepA, voffA);
;             PG8_WAIT_V(8); PG8_WAIT_L(0); PG8_BAR; PG8_MMA(0, 0, At, B0); if constexpr (!HALFN) PG8_MMA(0, 1, At, B1); PG8_BAR; PG8_SCHED;
;             PG8_LDA(At, 0, 1); PG8_STAGE(PG8_SB(0, 0), b2, voffB); PG8_STAGE(PG8_SB(0, 1), b2 + hstep, voffB); PG8_STAGE(PG8_SA(0, 0), a2, voffA);
.LBB0_806:
	s_add_u32 s18, s16, 0xfffe0080
	s_addc_u32 s19, s17, -1
	s_add_i32 s57, 0, 0x10000
	s_cmp_eq_u32 s53, 4
	s_cselect_b32 s21, s11, s19
	s_cselect_b32 s20, s10, s18
	s_cselect_b32 s19, s13, s52
	s_cselect_b32 s18, s12, s45
	s_add_i32 s72, 0, 0x14000
	v_add_u32_e32 v128, s57, v220
	v_add_u32_e32 v156, s72, v220
	ds_read_b128 v[112:115], v128
	ds_read_b128 v[116:119], v128 offset:1024
	ds_read_b128 v[120:123], v128 offset:2048
	ds_read_b128 v[128:131], v128 offset:3072
	ds_read_b128 v[136:139], v156
	ds_read_b128 v[140:143], v156 offset:1024
	ds_read_b128 v[144:147], v156 offset:2048
	ds_read_b128 v[156:159], v156 offset:3072
	s_add_i32 m0, s29, 0xc000
	ds_read_b128 v[160:163], v226
	ds_read_b128 v[164:167], v226 offset:1024
	ds_read_b128 v[168:171], v226 offset:2048
	ds_read_b128 v[172:175], v226 offset:3072
	ds_read_b128 v[176:179], v226 offset:4096
	ds_read_b128 v[180:183], v226 offset:5120
	ds_read_b128 v[184:187], v226 offset:6144
	ds_read_b128 v[204:207], v226 offset:7168
	global_load_lds_dwordx4 v198, s[16:17]
	s_add_i32 m0, s29, 0xe000
	s_nop 0
	global_load_lds_dwordx4 v196, s[16:17]
	s_waitcnt vmcnt(8)
	s_waitcnt lgkmcnt(0)
	s_barrier
	s_setprio 1
	s_waitcnt lgkmcnt(0)
	v_mfma_f32_16x16x32_bf16 v[152:155], v[112:115], v[160:163], v[152:155]
	v_mfma_f32_16x16x32_bf16 v[148:151], v[120:123], v[160:163], v[148:151]
	v_mfma_f32_16x16x32_bf16 v[108:111], v[112:115], v[168:171], v[108:111]
	v_mfma_f32_16x16x32_bf16 v[104:107], v[120:123], v[168:171], v[104:107]
	v_mfma_f32_16x16x32_bf16 v[92:95], v[112:115], v[176:179], v[92:95]
	v_mfma_f32_16x16x32_bf16 v[88:91], v[120:123], v[176:179], v[88:91]
	v_mfma_f32_16x16x32_bf16 v[76:79], v[112:115], v[184:187], v[76:79]
	v_mfma_f32_16x16x32_bf16 v[72:75], v[120:123], v[184:187], v[72:75]
	v_mfma_f32_16x16x32_bf16 v[152:155], v[116:119], v[164:167], v[152:155]
	v_mfma_f32_16x16x32_bf16 v[148:151], v[128:131], v[164:167], v[148:151]
	v_mfma_f32_16x16x32_bf16 v[108:111], v[116:119], v[172:175], v[108:111]
	v_mfma_f32_16x16x32_bf16 v[104:107], v[128:131], v[172:175], v[104:107]
	v_mfma_f32_16x16x32_bf16 v[92:95], v[116:119], v[180:183], v[92:95]
	v_mfma_f32_16x16x32_bf16 v[88:91], v[128:131], v[180:183], v[88:91]
	v_mfma_f32_16x16x32_bf16 v[76:79], v[116:119], v[204:207], v[76:79]
	v_mfma_f32_16x16x32_bf16 v[72:75], v[128:131], v[204:207], v[72:75]
	s_setprio 0
	s_setprio 1
	v_mfma_f32_16x16x32_bf16 v[132:135], v[136:139], v[160:163], v[132:135]
	v_mfma_f32_16x16x32_bf16 v[124:127], v[144:147], v[160:163], v[124:127]
	v_mfma_f32_16x16x32_bf16 v[100:103], v[136:139], v[168:171], v[100:103]
	v_mfma_f32_16x16x32_bf16 v[96:99], v[144:147], v[168:171], v[96:99]
	v_mfma_f32_16x16x32_bf16 v[84:87], v[136:139], v[176:179], v[84:87]
	v_mfma_f32_16x16x32_bf16 v[80:83], v[144:147], v[176:179], v[80:83]
	v_mfma_f32_16x16x32_bf16 v[68:71], v[136:139], v[184:187], v[68:71]
	v_mfma_f32_16x16x32_bf16 v[64:67], v[144:147], v[184:187], v[64:67]
	v_mfma_f32_16x16x32_bf16 v[132:135], v[140:143], v[164:167], v[132:135]
	v_mfma_f32_16x16x32_bf16 v[124:127], v[156:159], v[164:167], v[124:127]
	v_mfma_f32_16x16x32_bf16 v[100:103], v[140:143], v[172:175], v[100:103]
	v_mfma_f32_16x16x32_bf16 v[96:99], v[156:159], v[172:175], v[96:99]
	v_mfma_f32_16x16x32_bf16 v[84:87], v[140:143], v[180:183], v[84:87]
	v_mfma_f32_16x16x32_bf16 v[80:83], v[156:159], v[180:183], v[80:83]
	v_mfma_f32_16x16x32_bf16 v[68:71], v[140:143], v[204:207], v[68:71]
	v_mfma_f32_16x16x32_bf16 v[64:67], v[156:159], v[204:207], v[64:67]
	s_setprio 0
	s_barrier
	s_add_i32 s57, s57, s28
	v_lshl_add_u64 v[208:209], s[18:19], 0, v[200:201]
	s_mov_b32 m0, s57
	ds_read_b128 v[160:163], v226 offset:16384
	ds_read_b128 v[164:167], v226 offset:17408
	ds_read_b128 v[168:171], v226 offset:18432
	ds_read_b128 v[172:175], v226 offset:19456
	ds_read_b128 v[176:179], v226 offset:20480
	ds_read_b128 v[180:183], v226 offset:21504
	ds_read_b128 v[184:187], v226 offset:22528
	ds_read_b128 v[204:207], v226 offset:23552
	global_load_lds_dwordx4 v[208:209], off
	s_add_i32 m0, s57, 0x2000
	s_add_u32 s70, s18, 0x20000
	v_lshl_add_u64 v[210:211], s[18:19], 0, v[192:193]
	s_addc_u32 s71, s19, 0
	s_add_i32 s57, s72, s28
	global_load_lds_dwordx4 v[210:211], off
	s_mov_b32 m0, s57
	v_lshl_add_u64 v[214:215], s[20:21], 0, v[190:191]
	global_load_lds_dwordx4 v200, s[70:71]
	s_add_i32 m0, s57, 0x2000
	s_nop 0
	global_load_lds_dwordx4 v192, s[70:71]
	v_lshl_add_u64 v[212:213], s[20:21], 0, v[188:189]
	s_mov_b32 m0, s29
	s_nop 0
	global_load_lds_dwordx4 v[212:213], off
	s_mov_b32 m0, s30
	s_nop 0
	global_load_lds_dwordx4 v[214:215], off
	s_waitcnt vmcnt(8)
	s_waitcnt lgkmcnt(0)
	s_barrier
; #define PG8_STAGE(bufoff, gbase, voff) do { _Pragma("unroll") for (int _i = 0; _i < 2; ++_i) \
;         __builtin_amdgcn_global_load_lds((const unsigned*)((const char*)(gbase) + (voff)[_i]), (LAS unsigned*)(lds + (bufoff) + ldsw + _i * 8192), 16, 0, 0); } while (0)
; #define PG8_LDA(dst, b, h) do { _Pragma("unroll") for (int m = 0; m < 4; ++m) _Pragma("unroll") for (int k = 0; k < 2; ++k) dst[m][k] = *(const LAS bf16x8*)(lds + PG8_SA(b, h) + aoff + m * 2048 + k * 1024); } while (0)
; #define PG8_LDB(dst, b, h) do { _Pragma("unroll") for (int n = 0; n < 2; ++n) _Pragma("unroll") for (int k = 0; k < 2; ++k) dst[n][k] = *(const LAS bf16x8*)(lds + PG8_SB(b, h) + boff + n * 2048 + k * 1024); } while (0)
; #define PG8_MMA(ai, bj, At, Bt) do { __builtin_amdgcn_s_setprio(1); _Pragma("unroll") for (int m = 0; m < 4; ++m) _Pragma("unroll") for (int n = 0; n < 2; ++n) _Pragma("unroll") for (int k = 0; k < 2; ++k) \
;         acc[ai][bj][m][n] = __builtin_amdgcn_mfma_f32_16x16x32_bf16(Bt[n][k], At[m][k], acc[ai][bj][m][n], 0, 0, 0); __builtin_amdgcn_s_setprio(0); } while (0)
; #define PG8_WAIT_V(n) asm volatile("s_waitcnt vmcnt(" #n ")" ::: "memory")
; #define PG8_WAIT_L(n) asm volatile("s_waitcnt lgkmcnt(" #n ")" ::: "memory")
; #define PG8_BAR __builtin_amdgcn_s_barrier()
; #define PG8_SCHED __builtin_amdgcn_sched_barrier(0)
; template <class Epi, class Sched, bool APERM = false, bool HALFN = false>
; __device__ __forceinline__ void gemm_phase(LAS unsigned char* lds, const int tid_in, const int K, const Sched& S, const Epi& E) {
;     ...
;             PG8_WAIT_V(8); PG8_WAIT_L(0); PG8_BAR; PG8_MMA(1, 0, At, B0); if constexpr (!HALFN) PG8_MMA(1, 1, At, B1); PG8_BAR; PG8_SCHED;
;             PG8_LDB(B0, 1, 0); PG8_LDB(B1, 1, 1); PG8_SCHED; PG8_LDA(At, 1, 0); PG8_STAGE(PG8_SA(0, 1), a2 + hstepA, voffA);
;             PG8_WAIT_V(8); PG8_WAIT_L(0); PG8_BAR; PG8_MMA(0, 0, At, B0); if constexpr (!HALFN) PG8_MMA(0, 1, At, B1); PG8_BAR; PG8_SCHED;
	s_setprio 1
	s_waitcnt lgkmcnt(0)
	v_mfma_f32_16x16x32_bf16 v[60:63], v[112:115], v[160:163], v[60:63]
	v_mfma_f32_16x16x32_bf16 v[56:59], v[120:123], v[160:163], v[56:59]
	v_mfma_f32_16x16x32_bf16 v[44:47], v[112:115], v[168:171], v[44:47]
	v_mfma_f32_16x16x32_bf16 v[40:43], v[120:123], v[168:171], v[40:43]
	v_mfma_f32_16x16x32_bf16 v[28:31], v[112:115], v[176:179], v[28:31]
	v_mfma_f32_16x16x32_bf16 v[24:27], v[120:123], v[176:179], v[24:27]
	v_mfma_f32_16x16x32_bf16 v[12:15], v[112:115], v[184:187], v[12:15]
	v_mfma_f32_16x16x32_bf16 v[8:11], v[120:123], v[184:187], v[8:11]
	v_mfma_f32_16x16x32_bf16 v[60:63], v[116:119], v[164:167], v[60:63]
	v_mfma_f32_16x16x32_bf16 v[56:59], v[128:131], v[164:167], v[56:59]
	v_mfma_f32_16x16x32_bf16 v[44:47], v[116:119], v[172:175], v[44:47]
	v_mfma_f32_16x16x32_bf16 v[40:43], v[128:131], v[172:175], v[40:43]
	v_mfma_f32_16x16x32_bf16 v[28:31], v[116:119], v[180:183], v[28:31]
	v_mfma_f32_16x16x32_bf16 v[24:27], v[128:131], v[180:183], v[24:27]
	v_mfma_f32_16x16x32_bf16 v[12:15], v[116:119], v[204:207], v[12:15]
	v_mfma_f32_16x16x32_bf16 v[8:11], v[128:131], v[204:207], v[8:11]
	s_setprio 0
	s_setprio 1
	v_mfma_f32_16x16x32_bf16 v[52:55], v[136:139], v[160:163], v[52:55]
	v_mfma_f32_16x16x32_bf16 v[48:51], v[144:147], v[160:163], v[48:51]
	v_mfma_f32_16x16x32_bf16 v[36:39], v[136:139], v[168:171], v[36:39]
	v_mfma_f32_16x16x32_bf16 v[32:35], v[144:147], v[168:171], v[32:35]
	v_mfma_f32_16x16x32_bf16 v[20:23], v[136:139], v[176:179], v[20:23]
	v_mfma_f32_16x16x32_bf16 v[16:19], v[144:147], v[176:179], v[16:19]
	v_mfma_f32_16x16x32_bf16 v[4:7], v[136:139], v[184:187], v[4:7]
	v_mfma_f32_16x16x32_bf16 v[0:3], v[144:147], v[184:187], v[0:3]
	v_mfma_f32_16x16x32_bf16 v[52:55], v[140:143], v[164:167], v[52:55]
	v_mfma_f32_16x16x32_bf16 v[48:51], v[156:159], v[164:167], v[48:51]
	v_mfma_f32_16x16x32_bf16 v[36:39], v[140:143], v[172:175], v[36:39]
	v_mfma_f32_16x16x32_bf16 v[32:35], v[156:159], v[172:175], v[32:35]
	v_mfma_f32_16x16x32_bf16 v[20:23], v[140:143], v[180:183], v[20:23]
	v_mfma_f32_16x16x32_bf16 v[16:19], v[156:159], v[180:183], v[16:19]
	v_mfma_f32_16x16x32_bf16 v[4:7], v[140:143], v[204:207], v[4:7]
	v_mfma_f32_16x16x32_bf16 v[0:3], v[156:159], v[204:207], v[0:3]
	s_setprio 0
	s_barrier
	s_add_i32 s57, 0, 0x18000
	s_add_i32 s70, 0, 0x1c000
	v_add_u32_e32 v128, s57, v220
	v_add_u32_e32 v156, s70, v220
	ds_read_b128 v[112:115], v128
	ds_read_b128 v[116:119], v128 offset:1024
	ds_read_b128 v[120:123], v128 offset:2048
	ds_read_b128 v[128:131], v128 offset:3072
	ds_read_b128 v[136:139], v156
	ds_read_b128 v[140:143], v156 offset:1024
	ds_read_b128 v[144:147], v156 offset:2048
	ds_read_b128 v[156:159], v156 offset:3072
	s_add_u32 s20, s20, 0x20000
	s_addc_u32 s21, s21, 0
	s_mov_b32 m0, s31
	ds_read_b128 v[160:163], v226 offset:32768
	ds_read_b128 v[164:167], v226 offset:33792
	ds_read_b128 v[168:171], v226 offset:34816
	ds_read_b128 v[172:175], v226 offset:35840
	ds_read_b128 v[176:179], v226 offset:36864
	ds_read_b128 v[180:183], v226 offset:37888
	ds_read_b128 v[184:187], v226 offset:38912
	ds_read_b128 v[204:207], v226 offset:39936
	global_load_lds_dwordx4 v188, s[20:21]
	s_mov_b32 m0, s34
	s_nop 0
	global_load_lds_dwordx4 v190, s[20:21]
	s_waitcnt vmcnt(8)
	s_waitcnt lgkmcnt(0)
	s_barrier
	s_setprio 1
	s_waitcnt lgkmcnt(0)
	v_mfma_f32_16x16x32_bf16 v[152:155], v[112:115], v[160:163], v[152:155]
	v_mfma_f32_16x16x32_bf16 v[148:151], v[120:123], v[160:163], v[148:151]
	v_mfma_f32_16x16x32_bf16 v[108:111], v[112:115], v[168:171], v[108:111]
	v_mfma_f32_16x16x32_bf16 v[104:107], v[120:123], v[168:171], v[104:107]
	v_mfma_f32_16x16x32_bf16 v[92:95], v[112:115], v[176:179], v[92:95]
	v_mfma_f32_16x16x32_bf16 v[88:91], v[120:123], v[176:179], v[88:91]
	v_mfma_f32_16x16x32_bf16 v[76:79], v[112:115], v[184:187], v[76:79]
	v_mfma_f32_16x16x32_bf16 v[72:75], v[120:123], v[184:187], v[72:75]
	v_mfma_f32_16x16x32_bf16 v[152:155], v[116:119], v[164:167], v[152:155]
	v_mfma_f32_16x16x32_bf16 v[148:151], v[128:131], v[164:167], v[148:151]
	v_mfma_f32_16x16x32_bf16 v[108:111], v[116:119], v[172:175], v[108:111]
	v_mfma_f32_16x16x32_bf16 v[104:107], v[128:131], v[172:175], v[104:107]
	v_mfma_f32_16x16x32_bf16 v[92:95], v[116:119], v[180:183], v[92:95]
	v_mfma_f32_16x16x32_bf16 v[88:91], v[128:131], v[180:183], v[88:91]
	v_mfma_f32_16x16x32_bf16 v[76:79], v[116:119], v[204:207], v[76:79]
	v_mfma_f32_16x16x32_bf16 v[72:75], v[128:131], v[204:207], v[72:75]
	s_setprio 0
	s_setprio 1
	v_mfma_f32_16x16x32_bf16 v[132:135], v[136:139], v[160:163], v[132:135]
	v_mfma_f32_16x16x32_bf16 v[124:127], v[144:147], v[160:163], v[124:127]
	v_mfma_f32_16x16x32_bf16 v[100:103], v[136:139], v[168:171], v[100:103]
	v_mfma_f32_16x16x32_bf16 v[96:99], v[144:147], v[168:171], v[96:99]
	v_mfma_f32_16x16x32_bf16 v[84:87], v[136:139], v[176:179], v[84:87]
	v_mfma_f32_16x16x32_bf16 v[80:83], v[144:147], v[176:179], v[80:83]
	v_mfma_f32_16x16x32_bf16 v[68:71], v[136:139], v[184:187], v[68:71]
	v_mfma_f32_16x16x32_bf16 v[64:67], v[144:147], v[184:187], v[64:67]
	v_mfma_f32_16x16x32_bf16 v[132:135], v[140:143], v[164:167], v[132:135]
	v_mfma_f32_16x16x32_bf16 v[124:127], v[156:159], v[164:167], v[124:127]
	v_mfma_f32_16x16x32_bf16 v[100:103], v[140:143], v[172:175], v[100:103]
	v_mfma_f32_16x16x32_bf16 v[96:99], v[156:159], v[172:175], v[96:99]
	v_mfma_f32_16x16x32_bf16 v[84:87], v[140:143], v[180:183], v[84:87]
	v_mfma_f32_16x16x32_bf16 v[80:83], v[156:159], v[180:183], v[80:83]
	v_mfma_f32_16x16x32_bf16 v[68:71], v[140:143], v[204:207], v[68:71]
	v_mfma_f32_16x16x32_bf16 v[64:67], v[156:159], v[204:207], v[64:67]
	s_setprio 0
	s_barrier
; #define PG8_STAGE(bufoff, gbase, voff) do { _Pragma("unroll") for (int _i = 0; _i < 2; ++_i) \
;         __builtin_amdgcn_global_load_lds((const unsigned*)((const char*)(gbase) + (voff)[_i]), (LAS unsigned*)(lds + (bufoff) + ldsw + _i * 8192), 16, 0, 0); } while (0)
; #define PG8_LDA(dst, b, h) do { _Pragma("unroll") for (int m = 0; m < 4; ++m) _Pragma("unroll") for (int k = 0; k < 2; ++k) dst[m][k] = *(const LAS bf16x8*)(lds + PG8_SA(b, h) + aoff + m * 2048 + k * 1024); } while (0)
; #define PG8_MMA(ai, bj, At, Bt) do { __builtin_amdgcn_s_setprio(1); _Pragma("unroll") for (int m = 0; m < 4; ++m) _Pragma("unroll") for (int n = 0; n < 2; ++n) _Pragma("unroll") for (int k = 0; k < 2; ++k) \
;         acc[ai][bj][m][n] = __builtin_amdgcn_mfma_f32_16x16x32_bf16(Bt[n][k], At[m][k], acc[ai][bj][m][n], 0, 0, 0); __builtin_amdgcn_s_setprio(0); } while (0)
; #define PG8_WAIT_V(n) asm volatile("s_waitcnt vmcnt(" #n ")" ::: "memory")
; #define PG8_WAIT_L(n) asm volatile("s_waitcnt lgkmcnt(" #n ")" ::: "memory")
; #define PG8_BAR __builtin_amdgcn_s_barrier()
; #define PG8_SCHED __builtin_amdgcn_sched_barrier(0)
; template <class Epi, class Sched, bool APERM = false, bool HALFN = false>
; __device__ __forceinline__ void gemm_phase(LAS unsigned char* lds, const int tid_in, const int K, const Sched& S, const Epi& E) {
;     ...
;             PG8_LDA(At, 1, 1); PG8_STAGE(PG8_SB(1, 0), b3, voffB); PG8_STAGE(PG8_SB(1, 1), b3 + hstep, voffB); PG8_STAGE(PG8_SA(1, 0), a3, voffA);
;             PG8_WAIT_V(8); PG8_WAIT_L(0); PG8_BAR; PG8_MMA(1, 0, At, B0); if constexpr (!HALFN) PG8_MMA(1, 1, At, B1); PG8_BAR; PG8_SCHED;
;         }
;         if (wr == 0) PG8_BAR;
	s_add_i32 s20, s57, s28
	v_lshl_add_u64 v[208:209], v[208:209], 0, s[78:79]
	s_mov_b32 m0, s20
	ds_read_b128 v[160:163], v226 offset:49152
	ds_read_b128 v[164:167], v226 offset:50176
	ds_read_b128 v[168:171], v226 offset:51200
	ds_read_b128 v[172:175], v226 offset:52224
	ds_read_b128 v[176:179], v226 offset:53248
	ds_read_b128 v[180:183], v226 offset:54272
	ds_read_b128 v[184:187], v226 offset:55296
	ds_read_b128 v[204:207], v226 offset:56320
	global_load_lds_dwordx4 v[208:209], off
	s_add_i32 m0, s20, 0x2000
	s_add_u32 s18, s18, 0x20080
	v_lshl_add_u64 v[208:209], v[210:211], 0, s[78:79]
	s_addc_u32 s19, s19, 0
	s_add_i32 s20, s70, s28
	global_load_lds_dwordx4 v[208:209], off
	s_mov_b32 m0, s20
	s_nop 0
	global_load_lds_dwordx4 v200, s[18:19]
	s_add_i32 m0, s20, 0x2000
	s_nop 0
	global_load_lds_dwordx4 v192, s[18:19]
	v_lshl_add_u64 v[208:209], v[212:213], 0, s[78:79]
	s_mov_b32 m0, s35
	s_nop 0
	global_load_lds_dwordx4 v[208:209], off
	v_lshl_add_u64 v[208:209], v[214:215], 0, s[78:79]
	s_mov_b32 m0, s38
	s_nop 0
	global_load_lds_dwordx4 v[208:209], off
	s_waitcnt vmcnt(8)
	s_waitcnt lgkmcnt(0)
	s_barrier
	s_setprio 1
	s_waitcnt lgkmcnt(0)
	v_mfma_f32_16x16x32_bf16 v[60:63], v[112:115], v[160:163], v[60:63]
	v_mfma_f32_16x16x32_bf16 v[56:59], v[120:123], v[160:163], v[56:59]
	v_mfma_f32_16x16x32_bf16 v[44:47], v[112:115], v[168:171], v[44:47]
	v_mfma_f32_16x16x32_bf16 v[40:43], v[120:123], v[168:171], v[40:43]
	v_mfma_f32_16x16x32_bf16 v[28:31], v[112:115], v[176:179], v[28:31]
	v_mfma_f32_16x16x32_bf16 v[24:27], v[120:123], v[176:179], v[24:27]
	v_mfma_f32_16x16x32_bf16 v[12:15], v[112:115], v[184:187], v[12:15]
	v_mfma_f32_16x16x32_bf16 v[8:11], v[120:123], v[184:187], v[8:11]
	v_mfma_f32_16x16x32_bf16 v[60:63], v[116:119], v[164:167], v[60:63]
	v_mfma_f32_16x16x32_bf16 v[56:59], v[128:131], v[164:167], v[56:59]
	v_mfma_f32_16x16x32_bf16 v[44:47], v[116:119], v[172:175], v[44:47]
	v_mfma_f32_16x16x32_bf16 v[40:43], v[128:131], v[172:175], v[40:43]
	v_mfma_f32_16x16x32_bf16 v[28:31], v[116:119], v[180:183], v[28:31]
	v_mfma_f32_16x16x32_bf16 v[24:27], v[128:131], v[180:183], v[24:27]
	v_mfma_f32_16x16x32_bf16 v[12:15], v[116:119], v[204:207], v[12:15]
	v_mfma_f32_16x16x32_bf16 v[8:11], v[128:131], v[204:207], v[8:11]
	s_setprio 0
	s_setprio 1
	v_mfma_f32_16x16x32_bf16 v[52:55], v[136:139], v[160:163], v[52:55]
	v_mfma_f32_16x16x32_bf16 v[48:51], v[144:147], v[160:163], v[48:51]
	v_mfma_f32_16x16x32_bf16 v[36:39], v[136:139], v[168:171], v[36:39]
	v_mfma_f32_16x16x32_bf16 v[32:35], v[144:147], v[168:171], v[32:35]
	v_mfma_f32_16x16x32_bf16 v[20:23], v[136:139], v[176:179], v[20:23]
	v_mfma_f32_16x16x32_bf16 v[16:19], v[144:147], v[176:179], v[16:19]
	v_mfma_f32_16x16x32_bf16 v[4:7], v[136:139], v[184:187], v[4:7]
	v_mfma_f32_16x16x32_bf16 v[0:3], v[144:147], v[184:187], v[0:3]
	v_mfma_f32_16x16x32_bf16 v[52:55], v[140:143], v[164:167], v[52:55]
	v_mfma_f32_16x16x32_bf16 v[48:51], v[156:159], v[164:167], v[48:51]
	v_mfma_f32_16x16x32_bf16 v[36:39], v[140:143], v[172:175], v[36:39]
	v_mfma_f32_16x16x32_bf16 v[32:35], v[156:159], v[172:175], v[32:35]
	v_mfma_f32_16x16x32_bf16 v[20:23], v[140:143], v[180:183], v[20:23]
	v_mfma_f32_16x16x32_bf16 v[16:19], v[156:159], v[180:183], v[16:19]
	v_mfma_f32_16x16x32_bf16 v[4:7], v[140:143], v[204:207], v[4:7]
	v_mfma_f32_16x16x32_bf16 v[0:3], v[156:159], v[204:207], v[0:3]
	s_setprio 0
	s_barrier
	s_add_i32 s53, s53, 2
	s_add_u32 s45, s45, 0x100
	s_addc_u32 s52, s52, 0
	s_add_u32 s16, s16, 0x100
	s_addc_u32 s17, s17, 0
	s_cmp_gt_u32 s53, 5
	s_cbranch_scc0 .LBB0_806
	s_and_b64 vcc, exec, s[8:9]
	s_cbranch_vccz .LBB0_809
	s_barrier

; #define PG8_STAGE(bufoff, gbase, voff) do { _Pragma("unroll") for (int _i = 0; _i < 2; ++_i) \
;         __builtin_amdgcn_global_load_lds((const unsigned*)((const char*)(gbase) + (voff)[_i]), (LAS unsigned*)(lds + (bufoff) + ldsw + _i * 8192), 16, 0, 0); } while (0)
; #define PG8_LDA(dst, b, h) do { _Pragma("unroll") for (int m = 0; m < 4; ++m) _Pragma("unroll") for (int k = 0; k < 2; ++k) dst[m][k] = *(const LAS bf16x8*)(lds + PG8_SA(b, h) + aoff + m * 2048 + k * 1024); } while (0)
; #define PG8_LDB(dst, b, h) do { _Pragma("unroll") for (int n = 0; n < 2; ++n) _Pragma("unroll") for (int k = 0; k < 2; ++k) dst[n][k] = *(const LAS bf16x8*)(lds + PG8_SB(b, h) + boff + n * 2048 + k * 1024); } while (0)
; #define PG8_MMA(ai, bj, At, Bt) do { __builtin_amdgcn_s_setprio(1); _Pragma("unroll") for (int m = 0; m < 4; ++m) _Pragma("unroll") for (int n = 0; n < 2; ++n) _Pragma("unroll") for (int k = 0; k < 2; ++k) \
;         acc[ai][bj][m][n] = __builtin_amdgcn_mfma_f32_16x16x32_bf16(Bt[n][k], At[m][k], acc[ai][bj][m][n], 0, 0, 0); __builtin_amdgcn_s_setprio(0); } while (0)
; #define PG8_WAIT_V(n) asm volatile("s_waitcnt vmcnt(" #n ")" ::: "memory")
; #define PG8_WAIT_L(n) asm volatile("s_waitcnt lgkmcnt(" #n ")" ::: "memory")
; template <class Epi, class Sched, bool APERM = false, bool HALFN = false>
; __device__ __forceinline__ void gemm_phase(LAS unsigned char* lds, const int tid_in, const int K, const Sched& S, const Epi& E) {
;     ...
;     for (;;) {
;         const bool has_next = S.next(ui + 1, nxt);
;         const char* nA = has_next ? nxt.A : cA; const char* nB = has_next ? nxt.B : cB;
;         for (int t = 0; t < nt; t += 2) {
;             const bool last = (t == nt - 2);
;             const char* a1 = cA + (size_t)(t + 1) * kstep;
;             const char* a2 = last ? nA : cA + (size_t)(t + 2) * kstep; const char* b2 = last ? nB : cB + (size_t)(t + 2) * kstep;
;             const char* a3 = a2 + kstep; const char* b3 = b2 + kstep;
;             PG8_LDB(B0, 0, 0); PG8_LDB(B1, 0, 1); PG8_SCHED; PG8_LDA(At, 0, 0); PG8_STAGE(PG8_SA(1, 1), a1 + hstepA, voffA);
;             PG8_WAIT_V(8); PG8_WAIT_L(0); PG8_BAR; PG8_MMA(0, 0, At, B0); if constexpr (!HALFN) PG8_MMA(0, 1, At, B1); PG8_BAR; PG8_SCHED;
;             PG8_LDA(At, 0, 1); PG8_STAGE(PG8_SB(0, 0), b2, voffB); PG8_STAGE(PG8_SB(0, 1), b2 + hstep, voffB); PG8_STAGE(PG8_SA(0, 0), a2, voffA);
.LBB0_1033:
	s_add_u32 s18, s16, 0x100
	s_addc_u32 s19, s17, 0
	s_add_i32 s71, 0, 0x10000
	s_cmpk_eq_i32 s70, 0x54
	s_cselect_b32 s23, s11, s19
	s_cselect_b32 s22, s10, s18
	s_cselect_b32 s21, s13, s57
	s_cselect_b32 s20, s12, s53
	s_add_i32 s72, 0, 0x14000
	v_add_u32_e32 v128, s71, v220
	v_add_u32_e32 v156, s72, v220
	ds_read_b128 v[112:115], v128
	ds_read_b128 v[116:119], v128 offset:1024
	ds_read_b128 v[120:123], v128 offset:2048
	ds_read_b128 v[128:131], v128 offset:3072
	ds_read_b128 v[136:139], v156
	ds_read_b128 v[140:143], v156 offset:1024
	ds_read_b128 v[144:147], v156 offset:2048
	ds_read_b128 v[156:159], v156 offset:3072
	v_lshl_add_u64 v[208:209], s[16:17], 0, v[198:199]
	s_add_i32 m0, s31, 0xc000
	ds_read_b128 v[160:163], v226
	ds_read_b128 v[164:167], v226 offset:1024
	ds_read_b128 v[168:171], v226 offset:2048
	ds_read_b128 v[172:175], v226 offset:3072
	ds_read_b128 v[176:179], v226 offset:4096
	ds_read_b128 v[180:183], v226 offset:5120
	ds_read_b128 v[184:187], v226 offset:6144
	ds_read_b128 v[204:207], v226 offset:7168
	global_load_lds_dwordx4 v[208:209], off
	v_lshl_add_u64 v[208:209], s[16:17], 0, v[196:197]
	s_add_i32 m0, s31, 0xe000
	s_nop 0
	global_load_lds_dwordx4 v[208:209], off
	s_waitcnt vmcnt(8)
	s_waitcnt lgkmcnt(0)
	s_barrier
	s_setprio 1
	s_waitcnt lgkmcnt(0)
	v_mfma_f32_16x16x32_bf16 v[152:155], v[112:115], v[160:163], v[152:155]
	v_mfma_f32_16x16x32_bf16 v[148:151], v[120:123], v[160:163], v[148:151]
	v_mfma_f32_16x16x32_bf16 v[108:111], v[112:115], v[168:171], v[108:111]
	v_mfma_f32_16x16x32_bf16 v[104:107], v[120:123], v[168:171], v[104:107]
	v_mfma_f32_16x16x32_bf16 v[92:95], v[112:115], v[176:179], v[92:95]
	v_mfma_f32_16x16x32_bf16 v[88:91], v[120:123], v[176:179], v[88:91]
	v_mfma_f32_16x16x32_bf16 v[76:79], v[112:115], v[184:187], v[76:79]
	v_mfma_f32_16x16x32_bf16 v[72:75], v[120:123], v[184:187], v[72:75]
	v_mfma_f32_16x16x32_bf16 v[152:155], v[116:119], v[164:167], v[152:155]
	v_mfma_f32_16x16x32_bf16 v[148:151], v[128:131], v[164:167], v[148:151]
	v_mfma_f32_16x16x32_bf16 v[108:111], v[116:119], v[172:175], v[108:111]
	v_mfma_f32_16x16x32_bf16 v[104:107], v[128:131], v[172:175], v[104:107]
	v_mfma_f32_16x16x32_bf16 v[92:95], v[116:119], v[180:183], v[92:95]
	v_mfma_f32_16x16x32_bf16 v[88:91], v[128:131], v[180:183], v[88:91]
	v_mfma_f32_16x16x32_bf16 v[76:79], v[116:119], v[204:207], v[76:79]
	v_mfma_f32_16x16x32_bf16 v[72:75], v[128:131], v[204:207], v[72:75]
	s_setprio 0
	s_setprio 1
	v_mfma_f32_16x16x32_bf16 v[132:135], v[136:139], v[160:163], v[132:135]
	v_mfma_f32_16x16x32_bf16 v[124:127], v[144:147], v[160:163], v[124:127]
	v_mfma_f32_16x16x32_bf16 v[100:103], v[136:139], v[168:171], v[100:103]
	v_mfma_f32_16x16x32_bf16 v[96:99], v[144:147], v[168:171], v[96:99]
	v_mfma_f32_16x16x32_bf16 v[84:87], v[136:139], v[176:179], v[84:87]
	v_mfma_f32_16x16x32_bf16 v[80:83], v[144:147], v[176:179], v[80:83]
	v_mfma_f32_16x16x32_bf16 v[68:71], v[136:139], v[184:187], v[68:71]
	v_mfma_f32_16x16x32_bf16 v[64:67], v[144:147], v[184:187], v[64:67]
	v_mfma_f32_16x16x32_bf16 v[132:135], v[140:143], v[164:167], v[132:135]
	v_mfma_f32_16x16x32_bf16 v[124:127], v[156:159], v[164:167], v[124:127]
	v_mfma_f32_16x16x32_bf16 v[100:103], v[140:143], v[172:175], v[100:103]
	v_mfma_f32_16x16x32_bf16 v[96:99], v[156:159], v[172:175], v[96:99]
	v_mfma_f32_16x16x32_bf16 v[84:87], v[140:143], v[180:183], v[84:87]
	v_mfma_f32_16x16x32_bf16 v[80:83], v[156:159], v[180:183], v[80:83]
	v_mfma_f32_16x16x32_bf16 v[68:71], v[140:143], v[204:207], v[68:71]
	v_mfma_f32_16x16x32_bf16 v[64:67], v[156:159], v[204:207], v[64:67]
	s_setprio 0
	s_barrier
	s_add_i32 s16, s71, s30
	v_lshl_add_u64 v[208:209], s[20:21], 0, v[200:201]
	s_mov_b32 m0, s16
	ds_read_b128 v[160:163], v226 offset:16384
	ds_read_b128 v[164:167], v226 offset:17408
	ds_read_b128 v[168:171], v226 offset:18432
	ds_read_b128 v[172:175], v226 offset:19456
	ds_read_b128 v[176:179], v226 offset:20480
	ds_read_b128 v[180:183], v226 offset:21504
	ds_read_b128 v[184:187], v226 offset:22528
	ds_read_b128 v[204:207], v226 offset:23552
	global_load_lds_dwordx4 v[208:209], off
	s_add_i32 m0, s16, 0x2000
	s_add_u32 s16, s20, 0x160000
	v_lshl_add_u64 v[210:211], s[20:21], 0, v[192:193]
	s_addc_u32 s17, s21, 0
	s_add_i32 s71, s72, s30
	global_load_lds_dwordx4 v[210:211], off
	s_mov_b32 m0, s71
	v_lshl_add_u64 v[214:215], s[22:23], 0, v[190:191]
	global_load_lds_dwordx4 v200, s[16:17]
	s_add_i32 m0, s71, 0x2000
	s_nop 0
	global_load_lds_dwordx4 v192, s[16:17]
	v_lshl_add_u64 v[212:213], s[22:23], 0, v[188:189]
	s_mov_b32 m0, s31
	s_nop 0
	global_load_lds_dwordx4 v[212:213], off
	s_mov_b32 m0, s34
	s_nop 0
	global_load_lds_dwordx4 v[214:215], off
	s_waitcnt vmcnt(8)
	s_waitcnt lgkmcnt(0)
	s_barrier
; #define PG8_STAGE(bufoff, gbase, voff) do { _Pragma("unroll") for (int _i = 0; _i < 2; ++_i) \
;         __builtin_amdgcn_global_load_lds((const unsigned*)((const char*)(gbase) + (voff)[_i]), (LAS unsigned*)(lds + (bufoff) + ldsw + _i * 8192), 16, 0, 0); } while (0)
; #define PG8_LDA(dst, b, h) do { _Pragma("unroll") for (int m = 0; m < 4; ++m) _Pragma("unroll") for (int k = 0; k < 2; ++k) dst[m][k] = *(const LAS bf16x8*)(lds + PG8_SA(b, h) + aoff + m * 2048 + k * 1024); } while (0)
; #define PG8_LDB(dst, b, h) do { _Pragma("unroll") for (int n = 0; n < 2; ++n) _Pragma("unroll") for (int k = 0; k < 2; ++k) dst[n][k] = *(const LAS bf16x8*)(lds + PG8_SB(b, h) + boff + n * 2048 + k * 1024); } while (0)
; #define PG8_MMA(ai, bj, At, Bt) do { __builtin_amdgcn_s_setprio(1); _Pragma("unroll") for (int m = 0; m < 4; ++m) _Pragma("unroll") for (int n = 0; n < 2; ++n) _Pragma("unroll") for (int k = 0; k < 2; ++k) \
;         acc[ai][bj][m][n] = __builtin_amdgcn_mfma_f32_16x16x32_bf16(Bt[n][k], At[m][k], acc[ai][bj][m][n], 0, 0, 0); __builtin_amdgcn_s_setprio(0); } while (0)
; #define PG8_WAIT_V(n) asm volatile("s_waitcnt vmcnt(" #n ")" ::: "memory")
; #define PG8_WAIT_L(n) asm volatile("s_waitcnt lgkmcnt(" #n ")" ::: "memory")
; #define PG8_BAR __builtin_amdgcn_s_barrier()
; #define PG8_SCHED __builtin_amdgcn_sched_barrier(0)
; template <class Epi, class Sched, bool APERM = false, bool HALFN = false>
; __device__ __forceinline__ void gemm_phase(LAS unsigned char* lds, const int tid_in, const int K, const Sched& S, const Epi& E) {
;     ...
;             PG8_WAIT_V(8); PG8_WAIT_L(0); PG8_BAR; PG8_MMA(1, 0, At, B0); if constexpr (!HALFN) PG8_MMA(1, 1, At, B1); PG8_BAR; PG8_SCHED;
;             PG8_LDB(B0, 1, 0); PG8_LDB(B1, 1, 1); PG8_SCHED; PG8_LDA(At, 1, 0); PG8_STAGE(PG8_SA(0, 1), a2 + hstepA, voffA);
;             PG8_WAIT_V(8); PG8_WAIT_L(0); PG8_BAR; PG8_MMA(0, 0, At, B0); if constexpr (!HALFN) PG8_MMA(0, 1, At, B1); PG8_BAR; PG8_SCHED;
	s_setprio 1
	s_waitcnt lgkmcnt(0)
	v_mfma_f32_16x16x32_bf16 v[60:63], v[112:115], v[160:163], v[60:63]
	v_mfma_f32_16x16x32_bf16 v[56:59], v[120:123], v[160:163], v[56:59]
	v_mfma_f32_16x16x32_bf16 v[44:47], v[112:115], v[168:171], v[44:47]
	v_mfma_f32_16x16x32_bf16 v[40:43], v[120:123], v[168:171], v[40:43]
	v_mfma_f32_16x16x32_bf16 v[28:31], v[112:115], v[176:179], v[28:31]
	v_mfma_f32_16x16x32_bf16 v[24:27], v[120:123], v[176:179], v[24:27]
	v_mfma_f32_16x16x32_bf16 v[12:15], v[112:115], v[184:187], v[12:15]
	v_mfma_f32_16x16x32_bf16 v[8:11], v[120:123], v[184:187], v[8:11]
	v_mfma_f32_16x16x32_bf16 v[60:63], v[116:119], v[164:167], v[60:63]
	v_mfma_f32_16x16x32_bf16 v[56:59], v[128:131], v[164:167], v[56:59]
	v_mfma_f32_16x16x32_bf16 v[44:47], v[116:119], v[172:175], v[44:47]
	v_mfma_f32_16x16x32_bf16 v[40:43], v[128:131], v[172:175], v[40:43]
	v_mfma_f32_16x16x32_bf16 v[28:31], v[116:119], v[180:183], v[28:31]
	v_mfma_f32_16x16x32_bf16 v[24:27], v[128:131], v[180:183], v[24:27]
	v_mfma_f32_16x16x32_bf16 v[12:15], v[116:119], v[204:207], v[12:15]
	v_mfma_f32_16x16x32_bf16 v[8:11], v[128:131], v[204:207], v[8:11]
	s_setprio 0
	s_setprio 1
	v_mfma_f32_16x16x32_bf16 v[52:55], v[136:139], v[160:163], v[52:55]
	v_mfma_f32_16x16x32_bf16 v[48:51], v[144:147], v[160:163], v[48:51]
	v_mfma_f32_16x16x32_bf16 v[36:39], v[136:139], v[168:171], v[36:39]
	v_mfma_f32_16x16x32_bf16 v[32:35], v[144:147], v[168:171], v[32:35]
	v_mfma_f32_16x16x32_bf16 v[20:23], v[136:139], v[176:179], v[20:23]
	v_mfma_f32_16x16x32_bf16 v[16:19], v[144:147], v[176:179], v[16:19]
	v_mfma_f32_16x16x32_bf16 v[4:7], v[136:139], v[184:187], v[4:7]
	v_mfma_f32_16x16x32_bf16 v[0:3], v[144:147], v[184:187], v[0:3]
	v_mfma_f32_16x16x32_bf16 v[52:55], v[140:143], v[164:167], v[52:55]
	v_mfma_f32_16x16x32_bf16 v[48:51], v[156:159], v[164:167], v[48:51]
	v_mfma_f32_16x16x32_bf16 v[36:39], v[140:143], v[172:175], v[36:39]
	v_mfma_f32_16x16x32_bf16 v[32:35], v[156:159], v[172:175], v[32:35]
	v_mfma_f32_16x16x32_bf16 v[20:23], v[140:143], v[180:183], v[20:23]
	v_mfma_f32_16x16x32_bf16 v[16:19], v[156:159], v[180:183], v[16:19]
	v_mfma_f32_16x16x32_bf16 v[4:7], v[140:143], v[204:207], v[4:7]
	v_mfma_f32_16x16x32_bf16 v[0:3], v[156:159], v[204:207], v[0:3]
	s_setprio 0
	s_barrier
	s_add_i32 s71, 0, 0x18000
	s_add_i32 s72, 0, 0x1c000
	v_add_u32_e32 v128, s71, v220
	v_add_u32_e32 v156, s72, v220
	ds_read_b128 v[112:115], v128
	ds_read_b128 v[116:119], v128 offset:1024
	ds_read_b128 v[120:123], v128 offset:2048
	ds_read_b128 v[128:131], v128 offset:3072
	ds_read_b128 v[136:139], v156
	ds_read_b128 v[140:143], v156 offset:1024
	ds_read_b128 v[144:147], v156 offset:2048
	ds_read_b128 v[156:159], v156 offset:3072
	s_add_u32 s16, s22, 0x160000
	s_addc_u32 s17, s23, 0
	s_mov_b32 m0, s35
	ds_read_b128 v[160:163], v226 offset:32768
	ds_read_b128 v[164:167], v226 offset:33792
	ds_read_b128 v[168:171], v226 offset:34816
	ds_read_b128 v[172:175], v226 offset:35840
	ds_read_b128 v[176:179], v226 offset:36864
	ds_read_b128 v[180:183], v226 offset:37888
	ds_read_b128 v[184:187], v226 offset:38912
	ds_read_b128 v[204:207], v226 offset:39936
	global_load_lds_dwordx4 v188, s[16:17]
	s_mov_b32 m0, s38
	s_nop 0
	global_load_lds_dwordx4 v190, s[16:17]
	s_waitcnt vmcnt(8)
	s_waitcnt lgkmcnt(0)
	s_barrier
	s_setprio 1
	s_waitcnt lgkmcnt(0)
	v_mfma_f32_16x16x32_bf16 v[152:155], v[112:115], v[160:163], v[152:155]
	v_mfma_f32_16x16x32_bf16 v[148:151], v[120:123], v[160:163], v[148:151]
	v_mfma_f32_16x16x32_bf16 v[108:111], v[112:115], v[168:171], v[108:111]
	v_mfma_f32_16x16x32_bf16 v[104:107], v[120:123], v[168:171], v[104:107]
	v_mfma_f32_16x16x32_bf16 v[92:95], v[112:115], v[176:179], v[92:95]
	v_mfma_f32_16x16x32_bf16 v[88:91], v[120:123], v[176:179], v[88:91]
	v_mfma_f32_16x16x32_bf16 v[76:79], v[112:115], v[184:187], v[76:79]
	v_mfma_f32_16x16x32_bf16 v[72:75], v[120:123], v[184:187], v[72:75]
	v_mfma_f32_16x16x32_bf16 v[152:155], v[116:119], v[164:167], v[152:155]
	v_mfma_f32_16x16x32_bf16 v[148:151], v[128:131], v[164:167], v[148:151]
	v_mfma_f32_16x16x32_bf16 v[108:111], v[116:119], v[172:175], v[108:111]
	v_mfma_f32_16x16x32_bf16 v[104:107], v[128:131], v[172:175], v[104:107]
	v_mfma_f32_16x16x32_bf16 v[92:95], v[116:119], v[180:183], v[92:95]
	v_mfma_f32_16x16x32_bf16 v[88:91], v[128:131], v[180:183], v[88:91]
	v_mfma_f32_16x16x32_bf16 v[76:79], v[116:119], v[204:207], v[76:79]
	v_mfma_f32_16x16x32_bf16 v[72:75], v[128:131], v[204:207], v[72:75]
	s_setprio 0
	s_setprio 1
	v_mfma_f32_16x16x32_bf16 v[132:135], v[136:139], v[160:163], v[132:135]
	v_mfma_f32_16x16x32_bf16 v[124:127], v[144:147], v[160:163], v[124:127]
	v_mfma_f32_16x16x32_bf16 v[100:103], v[136:139], v[168:171], v[100:103]
	v_mfma_f32_16x16x32_bf16 v[96:99], v[144:147], v[168:171], v[96:99]
	v_mfma_f32_16x16x32_bf16 v[84:87], v[136:139], v[176:179], v[84:87]
	v_mfma_f32_16x16x32_bf16 v[80:83], v[144:147], v[176:179], v[80:83]
	v_mfma_f32_16x16x32_bf16 v[68:71], v[136:139], v[184:187], v[68:71]
	v_mfma_f32_16x16x32_bf16 v[64:67], v[144:147], v[184:187], v[64:67]
	v_mfma_f32_16x16x32_bf16 v[132:135], v[140:143], v[164:167], v[132:135]
	v_mfma_f32_16x16x32_bf16 v[124:127], v[156:159], v[164:167], v[124:127]
	v_mfma_f32_16x16x32_bf16 v[100:103], v[140:143], v[172:175], v[100:103]
	v_mfma_f32_16x16x32_bf16 v[96:99], v[156:159], v[172:175], v[96:99]
	v_mfma_f32_16x16x32_bf16 v[84:87], v[140:143], v[180:183], v[84:87]
	v_mfma_f32_16x16x32_bf16 v[80:83], v[156:159], v[180:183], v[80:83]
	v_mfma_f32_16x16x32_bf16 v[68:71], v[140:143], v[204:207], v[68:71]
	v_mfma_f32_16x16x32_bf16 v[64:67], v[156:159], v[204:207], v[64:67]
	s_setprio 0
	s_barrier
; #define PG8_STAGE(bufoff, gbase, voff) do { _Pragma("unroll") for (int _i = 0; _i < 2; ++_i) \
;         __builtin_amdgcn_global_load_lds((const unsigned*)((const char*)(gbase) + (voff)[_i]), (LAS unsigned*)(lds + (bufoff) + ldsw + _i * 8192), 16, 0, 0); } while (0)
; #define PG8_LDA(dst, b, h) do { _Pragma("unroll") for (int m = 0; m < 4; ++m) _Pragma("unroll") for (int k = 0; k < 2; ++k) dst[m][k] = *(const LAS bf16x8*)(lds + PG8_SA(b, h) + aoff + m * 2048 + k * 1024); } while (0)
; #define PG8_MMA(ai, bj, At, Bt) do { __builtin_amdgcn_s_setprio(1); _Pragma("unroll") for (int m = 0; m < 4; ++m) _Pragma("unroll") for (int n = 0; n < 2; ++n) _Pragma("unroll") for (int k = 0; k < 2; ++k) \
;         acc[ai][bj][m][n] = __builtin_amdgcn_mfma_f32_16x16x32_bf16(Bt[n][k], At[m][k], acc[ai][bj][m][n], 0, 0, 0); __builtin_amdgcn_s_setprio(0); } while (0)
; #define PG8_WAIT_V(n) asm volatile("s_waitcnt vmcnt(" #n ")" ::: "memory")
; #define PG8_WAIT_L(n) asm volatile("s_waitcnt lgkmcnt(" #n ")" ::: "memory")
; #define PG8_BAR __builtin_amdgcn_s_barrier()
; #define PG8_SCHED __builtin_amdgcn_sched_barrier(0)
; template <class Epi, class Sched, bool APERM = false, bool HALFN = false>
; __device__ __forceinline__ void gemm_phase(LAS unsigned char* lds, const int tid_in, const int K, const Sched& S, const Epi& E) {
;     ...
;             PG8_LDA(At, 1, 1); PG8_STAGE(PG8_SB(1, 0), b3, voffB); PG8_STAGE(PG8_SB(1, 1), b3 + hstep, voffB); PG8_STAGE(PG8_SA(1, 0), a3, voffA);
;             PG8_WAIT_V(8); PG8_WAIT_L(0); PG8_BAR; PG8_MMA(1, 0, At, B0); if constexpr (!HALFN) PG8_MMA(1, 1, At, B1); PG8_BAR; PG8_SCHED;
;         }
;         if (wr == 0) PG8_BAR;
	s_add_i32 s16, s71, s30
	v_lshl_add_u64 v[208:209], v[208:209], 0, s[78:79]
	s_mov_b32 m0, s16
	ds_read_b128 v[160:163], v226 offset:49152
	ds_read_b128 v[164:167], v226 offset:50176
	ds_read_b128 v[168:171], v226 offset:51200
	ds_read_b128 v[172:175], v226 offset:52224
	ds_read_b128 v[176:179], v226 offset:53248
	ds_read_b128 v[180:183], v226 offset:54272
	ds_read_b128 v[184:187], v226 offset:55296
	ds_read_b128 v[204:207], v226 offset:56320
	global_load_lds_dwordx4 v[208:209], off
	s_add_i32 m0, s16, 0x2000
	s_add_u32 s16, s20, 0x160080
	v_lshl_add_u64 v[208:209], v[210:211], 0, s[78:79]
	s_addc_u32 s17, s21, 0
	s_add_i32 s20, s72, s30
	global_load_lds_dwordx4 v[208:209], off
	s_mov_b32 m0, s20
	s_nop 0
	global_load_lds_dwordx4 v200, s[16:17]
	s_add_i32 m0, s20, 0x2000
	s_nop 0
	global_load_lds_dwordx4 v192, s[16:17]
	v_lshl_add_u64 v[208:209], v[212:213], 0, s[78:79]
	s_mov_b32 m0, s39
	s_nop 0
	global_load_lds_dwordx4 v[208:209], off
	v_lshl_add_u64 v[208:209], v[214:215], 0, s[78:79]
	s_mov_b32 m0, s44
	s_nop 0
	global_load_lds_dwordx4 v[208:209], off
	s_waitcnt vmcnt(8)
	s_waitcnt lgkmcnt(0)
	s_barrier
	s_setprio 1
	s_waitcnt lgkmcnt(0)
	v_mfma_f32_16x16x32_bf16 v[60:63], v[112:115], v[160:163], v[60:63]
	v_mfma_f32_16x16x32_bf16 v[56:59], v[120:123], v[160:163], v[56:59]
	v_mfma_f32_16x16x32_bf16 v[44:47], v[112:115], v[168:171], v[44:47]
	v_mfma_f32_16x16x32_bf16 v[40:43], v[120:123], v[168:171], v[40:43]
	v_mfma_f32_16x16x32_bf16 v[28:31], v[112:115], v[176:179], v[28:31]
	v_mfma_f32_16x16x32_bf16 v[24:27], v[120:123], v[176:179], v[24:27]
	v_mfma_f32_16x16x32_bf16 v[12:15], v[112:115], v[184:187], v[12:15]
	v_mfma_f32_16x16x32_bf16 v[8:11], v[120:123], v[184:187], v[8:11]
	v_mfma_f32_16x16x32_bf16 v[60:63], v[116:119], v[164:167], v[60:63]
	v_mfma_f32_16x16x32_bf16 v[56:59], v[128:131], v[164:167], v[56:59]
	v_mfma_f32_16x16x32_bf16 v[44:47], v[116:119], v[172:175], v[44:47]
	v_mfma_f32_16x16x32_bf16 v[40:43], v[128:131], v[172:175], v[40:43]
	v_mfma_f32_16x16x32_bf16 v[28:31], v[116:119], v[180:183], v[28:31]
	v_mfma_f32_16x16x32_bf16 v[24:27], v[128:131], v[180:183], v[24:27]
	v_mfma_f32_16x16x32_bf16 v[12:15], v[116:119], v[204:207], v[12:15]
	v_mfma_f32_16x16x32_bf16 v[8:11], v[128:131], v[204:207], v[8:11]
	s_setprio 0
	s_setprio 1
	v_mfma_f32_16x16x32_bf16 v[52:55], v[136:139], v[160:163], v[52:55]
	v_mfma_f32_16x16x32_bf16 v[48:51], v[144:147], v[160:163], v[48:51]
	v_mfma_f32_16x16x32_bf16 v[36:39], v[136:139], v[168:171], v[36:39]
	v_mfma_f32_16x16x32_bf16 v[32:35], v[144:147], v[168:171], v[32:35]
	v_mfma_f32_16x16x32_bf16 v[20:23], v[136:139], v[176:179], v[20:23]
	v_mfma_f32_16x16x32_bf16 v[16:19], v[144:147], v[176:179], v[16:19]
	v_mfma_f32_16x16x32_bf16 v[4:7], v[136:139], v[184:187], v[4:7]
	v_mfma_f32_16x16x32_bf16 v[0:3], v[144:147], v[184:187], v[0:3]
	v_mfma_f32_16x16x32_bf16 v[52:55], v[140:143], v[164:167], v[52:55]
	v_mfma_f32_16x16x32_bf16 v[48:51], v[156:159], v[164:167], v[48:51]
	v_mfma_f32_16x16x32_bf16 v[36:39], v[140:143], v[172:175], v[36:39]
	v_mfma_f32_16x16x32_bf16 v[32:35], v[156:159], v[172:175], v[32:35]
	v_mfma_f32_16x16x32_bf16 v[20:23], v[140:143], v[180:183], v[20:23]
	v_mfma_f32_16x16x32_bf16 v[16:19], v[156:159], v[180:183], v[16:19]
	v_mfma_f32_16x16x32_bf16 v[4:7], v[140:143], v[204:207], v[4:7]
	v_mfma_f32_16x16x32_bf16 v[0:3], v[156:159], v[204:207], v[0:3]
	s_setprio 0
	s_barrier
	s_add_i32 s70, s70, 2
	s_add_u32 s53, s53, 0x100
	s_addc_u32 s57, s57, 0
	s_cmpk_gt_u32 s70, 0x55
	s_mov_b64 s[16:17], s[18:19]
	s_cbranch_scc0 .LBB0_1033
	s_and_b64 vcc, exec, s[8:9]
	s_cbranch_vccz .LBB0_1036
	s_barrier
